# v15 plus next-tile first DMA issued before the wait on the row-statistics loads in the projection epilogue
# baseline (speedup 1.0000x reference)
.Lpe_notv_L0:
	s_cmp_ge_u32 s25, 9
	s_cbranch_scc1 .Lpe_gates_L0
	s_lshr_b32 s34, s25, 1
	s_cmp_ge_u32 s25, 6
	s_cselect_b32 s35, 1, 0
	s_sub_u32 s34, s34, s35
	s_lshl_b32 s35, s98, 2
	s_add_u32 s35, s35, s34
	s_lshl_b32 s35, s35, 8
	v_readlane_b32 s82, v254, 14
	v_readlane_b32 s83, v254, 15
	s_add_u32 s82, s82, s35
	s_addc_u32 s83, s83, 0
	global_load_dwordx4 v[198:201], v146, s[82:83] offset:0
	global_load_dwordx4 v[202:205], v146, s[82:83] offset:32
	global_load_dwordx4 v[206:209], v146, s[82:83] offset:64
	global_load_dwordx4 v[210:213], v146, s[82:83] offset:96
	global_load_dwordx4 v[214:217], v146, s[82:83] offset:128
	global_load_dwordx4 v[218:221], v146, s[82:83] offset:160
	global_load_dwordx4 v[222:225], v146, s[82:83] offset:192
	global_load_dwordx4 v[226:229], v146, s[82:83] offset:224
	s_and_b32 s35, s34, 1
	s_cmp_eq_u32 s35, 0
	s_cselect_b32 s36, 0x3e000000, 1.0
	s_and_b32 s35, s29, 0x7ff
	s_lshl_b32 s35, s35, 7
	s_add_u32 s96, s72, 0x1ada0000
	s_addc_u32 s97, s73, 0
	s_add_u32 s96, s96, s35
	s_addc_u32 s97, s97, 0
	s_add_u32 s100, s96, 0x40000
	s_addc_u32 s101, s97, 0
	s_cmp_ge_u32 s34, 2
	s_cselect_b32 s37, 1, 0
	s_add_u32 s76, s99, s90
	s_cmp_lt_u32 s76, 0x440
	s_cselect_b32 s80, 1, 0
	s_cselect_b32 s83, 0x200000, 0
	s_lshl_b32 s76, s24, 19
	s_lshl_b32 s77, s26, 16
	s_add_u32 s76, s76, s77
	s_and_b32 s77, s24, 7
	s_lshl_b32 s77, s77, 8
	s_add_u32 s76, s76, s77
	s_add_u32 s78, s72, 0xa120000
	s_addc_u32 s79, s73, 0
	s_add_u32 s78, s78, s76
	s_addc_u32 s79, s79, 0
	s_lshl_b32 s76, s25, 19
	s_add_u32 s76, s76, s83
	s_add_u32 s76, s76, s77
	s_lshl_b32 s77, s26, 16
	s_add_u32 s76, s76, s77
	s_add_u32 s82, s72, 0x0
	s_addc_u32 s83, s73, 0
	s_add_u32 s82, s82, s76
	s_addc_u32 s83, s83, 0
	s_lshl_b32 s76, s26, 12
	s_mov_b32 m0, s76
	s_nop 0
	global_load_lds_dwordx4 v145, s[78:79]
	s_add_u32 s78, s78, 0x4000
	s_addc_u32 s79, s79, 0
	s_add_u32 s76, s76, 0x400
	s_mov_b32 m0, s76
	s_nop 0
	global_load_lds_dwordx4 v185, s[78:79]
	s_add_u32 s78, s78, 0x4000
	s_addc_u32 s79, s79, 0
	s_add_u32 s76, s76, 0x400
	s_mov_b32 m0, s76
	s_nop 0
	global_load_lds_dwordx4 v145, s[78:79]
	s_add_u32 s78, s78, 0x4000
	s_addc_u32 s79, s79, 0
	s_add_u32 s76, s76, 0x400
	s_mov_b32 m0, s76
	s_nop 0
	global_load_lds_dwordx4 v185, s[78:79]
	s_add_u32 s78, s78, 0x4000
	s_addc_u32 s79, s79, 0
	s_add_u32 s76, s76, 0x400
	s_add_u32 s76, s76, 0x7000
	s_mov_b32 m0, s76
	s_nop 0
	global_load_lds_dwordx4 v145, s[82:83]
	s_add_u32 s82, s82, 0x4000
	s_addc_u32 s83, s83, 0
	s_add_u32 s76, s76, 0x400
	s_mov_b32 m0, s76
	s_nop 0
	global_load_lds_dwordx4 v185, s[82:83]
	s_add_u32 s82, s82, 0x4000
	s_addc_u32 s83, s83, 0
	s_add_u32 s76, s76, 0x400
	s_mov_b32 m0, s76
	s_nop 0
	global_load_lds_dwordx4 v145, s[82:83]
	s_add_u32 s82, s82, 0x4000
	s_addc_u32 s83, s83, 0
	s_add_u32 s76, s76, 0x400
	s_mov_b32 m0, s76
	s_nop 0
	global_load_lds_dwordx4 v185, s[82:83]
	s_add_u32 s82, s82, 0x4000
	s_addc_u32 s83, s83, 0
	s_add_u32 s76, s76, 0x400
	s_waitcnt vmcnt(16)
	v_lshlrev_b32_e32 v180, 7, v197
	v_add_u32_e32 v180, v180, v146
	v_mov_b32_e32 v197, 0x358637bd
	v_pk_add_f32 v[128:129], v[128:129], v[130:131]
	v_pk_add_f32 v[132:133], v[132:133], v[134:135]
	v_pk_add_f32 v[136:137], v[136:137], v[138:139]
	v_pk_add_f32 v[140:141], v[140:141], v[142:143]
	v_pk_add_f32 v[164:165], v[164:165], v[166:167]
	v_pk_add_f32 v[168:169], v[168:169], v[170:171]
	v_pk_add_f32 v[246:247], v[246:247], v[248:249]
	v_pk_add_f32 v[250:251], v[250:251], v[252:253]
	v_pk_add_f32 v[128:129], v[128:129], v[132:133]
	v_pk_add_f32 v[136:137], v[136:137], v[140:141]
	v_pk_add_f32 v[164:165], v[164:165], v[168:169]
	v_pk_add_f32 v[246:247], v[246:247], v[250:251]
	v_add_f32_e32 v128, v128, v129
	v_add_f32_e32 v136, v136, v137
	v_add_f32_e32 v164, v164, v165
	v_add_f32_e32 v246, v246, v247
	v_fmamk_f32 v128, v128, 0x3a800000, v197
	v_fmamk_f32 v136, v136, 0x3a800000, v197
	v_fmamk_f32 v164, v164, 0x3a800000, v197
	v_fmamk_f32 v246, v246, 0x3a800000, v197
	v_rsq_f32_e32 v172, v128
	v_rsq_f32_e32 v173, v136
	v_rsq_f32_e32 v174, v164
	v_rsq_f32_e32 v175, v246
	s_nop 0
	s_cmp_eq_u32 s37, 0
	s_cbranch_scc1 .Lpe_norope_ld_L0
	global_load_dwordx4 v[230:233], v180, s[96:97] offset:0
	global_load_dwordx4 v[234:237], v180, s[96:97] offset:32
	global_load_dwordx4 v[238:241], v180, s[96:97] offset:64
	global_load_dwordx4 v[242:245], v180, s[96:97] offset:96
	global_load_dwordx4 v[148:151], v180, s[100:101] offset:0
	global_load_dwordx4 v[152:155], v180, s[100:101] offset:32
	global_load_dwordx4 v[156:159], v180, s[100:101] offset:64
	global_load_dwordx4 v[160:163], v180, s[100:101] offset:96

.Lpe_gates_L0:
	s_lshl_b32 s35, s98, 11
	s_add_u32 s35, s35, s30
	s_sub_u32 s35, s35, 0x900
	s_lshl_b32 s35, s35, 2
	v_readlane_b32 s82, v254, 12
	v_readlane_b32 s83, v254, 13
	s_add_u32 s82, s82, s35
	s_addc_u32 s83, s83, 0
	global_load_dwordx4 v[198:201], v146, s[82:83] offset:0
	global_load_dwordx4 v[202:205], v146, s[82:83] offset:32
	global_load_dwordx4 v[206:209], v146, s[82:83] offset:64
	global_load_dwordx4 v[210:213], v146, s[82:83] offset:96
	global_load_dwordx4 v[214:217], v146, s[82:83] offset:128
	global_load_dwordx4 v[218:221], v146, s[82:83] offset:160
	global_load_dwordx4 v[222:225], v146, s[82:83] offset:192
	global_load_dwordx4 v[226:229], v146, s[82:83] offset:224
	s_add_u32 s76, s99, s90
	s_cmp_lt_u32 s76, 0x440
	s_cselect_b32 s80, 1, 0
	s_cselect_b32 s83, 0x200000, 0
	s_lshl_b32 s76, s24, 19
	s_lshl_b32 s77, s26, 16
	s_add_u32 s76, s76, s77
	s_and_b32 s77, s24, 7
	s_lshl_b32 s77, s77, 8
	s_add_u32 s76, s76, s77
	s_add_u32 s78, s72, 0xa120000
	s_addc_u32 s79, s73, 0
	s_add_u32 s78, s78, s76
	s_addc_u32 s79, s79, 0
	s_lshl_b32 s76, s25, 19
	s_add_u32 s76, s76, s83
	s_add_u32 s76, s76, s77
	s_lshl_b32 s77, s26, 16
	s_add_u32 s76, s76, s77
	s_add_u32 s82, s72, 0x0
	s_addc_u32 s83, s73, 0
	s_add_u32 s82, s82, s76
	s_addc_u32 s83, s83, 0
	s_lshl_b32 s76, s26, 12
	s_mov_b32 m0, s76
	s_nop 0
	global_load_lds_dwordx4 v145, s[78:79]
	s_add_u32 s78, s78, 0x4000
	s_addc_u32 s79, s79, 0
	s_add_u32 s76, s76, 0x400
	s_mov_b32 m0, s76
	s_nop 0
	global_load_lds_dwordx4 v185, s[78:79]
	s_add_u32 s78, s78, 0x4000
	s_addc_u32 s79, s79, 0
	s_add_u32 s76, s76, 0x400
	s_mov_b32 m0, s76
	s_nop 0
	global_load_lds_dwordx4 v145, s[78:79]
	s_add_u32 s78, s78, 0x4000
	s_addc_u32 s79, s79, 0
	s_add_u32 s76, s76, 0x400
	s_mov_b32 m0, s76
	s_nop 0
	global_load_lds_dwordx4 v185, s[78:79]
	s_add_u32 s78, s78, 0x4000
	s_addc_u32 s79, s79, 0
	s_add_u32 s76, s76, 0x400
	s_add_u32 s76, s76, 0x7000
	s_mov_b32 m0, s76
	s_nop 0
	global_load_lds_dwordx4 v145, s[82:83]
	s_add_u32 s82, s82, 0x4000
	s_addc_u32 s83, s83, 0
	s_add_u32 s76, s76, 0x400
	s_mov_b32 m0, s76
	s_nop 0
	global_load_lds_dwordx4 v185, s[82:83]
	s_add_u32 s82, s82, 0x4000
	s_addc_u32 s83, s83, 0
	s_add_u32 s76, s76, 0x400
	s_mov_b32 m0, s76
	s_nop 0
	global_load_lds_dwordx4 v145, s[82:83]
	s_add_u32 s82, s82, 0x4000
	s_addc_u32 s83, s83, 0
	s_add_u32 s76, s76, 0x400
	s_mov_b32 m0, s76
	s_nop 0
	global_load_lds_dwordx4 v185, s[82:83]
	s_add_u32 s82, s82, 0x4000
	s_addc_u32 s83, s83, 0
	s_add_u32 s76, s76, 0x400
	s_waitcnt vmcnt(16)
	v_mov_b32_e32 v197, 0x358637bd
	v_pk_add_f32 v[128:129], v[128:129], v[130:131]
	v_pk_add_f32 v[132:133], v[132:133], v[134:135]
	v_pk_add_f32 v[136:137], v[136:137], v[138:139]
	v_pk_add_f32 v[140:141], v[140:141], v[142:143]
	v_pk_add_f32 v[164:165], v[164:165], v[166:167]
	v_pk_add_f32 v[168:169], v[168:169], v[170:171]
	v_pk_add_f32 v[246:247], v[246:247], v[248:249]
	v_pk_add_f32 v[250:251], v[250:251], v[252:253]
	v_pk_add_f32 v[128:129], v[128:129], v[132:133]
	v_pk_add_f32 v[136:137], v[136:137], v[140:141]
	v_pk_add_f32 v[164:165], v[164:165], v[168:169]
	v_pk_add_f32 v[246:247], v[246:247], v[250:251]
	v_add_f32_e32 v128, v128, v129
	v_add_f32_e32 v136, v136, v137
	v_add_f32_e32 v164, v164, v165
	v_add_f32_e32 v246, v246, v247
	v_fmamk_f32 v128, v128, 0x3a800000, v197
	v_fmamk_f32 v136, v136, 0x3a800000, v197
	v_fmamk_f32 v164, v164, 0x3a800000, v197
	v_fmamk_f32 v246, v246, 0x3a800000, v197
	v_rsq_f32_e32 v172, v128
	v_rsq_f32_e32 v173, v136
	v_rsq_f32_e32 v174, v164
	v_rsq_f32_e32 v175, v246
	s_nop 0
	v_mul_f32_e32 v172, 0xbfb8aa3b, v172
	v_mul_f32_e32 v173, 0xbfb8aa3b, v173
	v_mul_f32_e32 v174, 0xbfb8aa3b, v174
	v_mul_f32_e32 v175, 0xbfb8aa3b, v175
	s_waitcnt vmcnt(8)
	v_mul_f32_e32 v198, 0xbfb8aa3b, v198
	v_mul_f32_e32 v199, 0xbfb8aa3b, v199
	v_mul_f32_e32 v200, 0xbfb8aa3b, v200
	v_mul_f32_e32 v201, 0xbfb8aa3b, v201
	v_mul_f32_e32 v202, 0xbfb8aa3b, v202
	v_mul_f32_e32 v203, 0xbfb8aa3b, v203
	v_mul_f32_e32 v204, 0xbfb8aa3b, v204
	v_mul_f32_e32 v205, 0xbfb8aa3b, v205
	v_mul_f32_e32 v206, 0xbfb8aa3b, v206
	v_mul_f32_e32 v207, 0xbfb8aa3b, v207
	v_mul_f32_e32 v208, 0xbfb8aa3b, v208
	v_mul_f32_e32 v209, 0xbfb8aa3b, v209
	v_mul_f32_e32 v210, 0xbfb8aa3b, v210
	v_mul_f32_e32 v211, 0xbfb8aa3b, v211
	v_mul_f32_e32 v212, 0xbfb8aa3b, v212
	v_mul_f32_e32 v213, 0xbfb8aa3b, v213
	v_mul_f32_e32 v214, 0xbfb8aa3b, v214
	v_mul_f32_e32 v215, 0xbfb8aa3b, v215
	v_mul_f32_e32 v216, 0xbfb8aa3b, v216
	v_mul_f32_e32 v217, 0xbfb8aa3b, v217
	v_mul_f32_e32 v218, 0xbfb8aa3b, v218
	v_mul_f32_e32 v219, 0xbfb8aa3b, v219
	v_mul_f32_e32 v220, 0xbfb8aa3b, v220
	v_mul_f32_e32 v221, 0xbfb8aa3b, v221
	v_mul_f32_e32 v222, 0xbfb8aa3b, v222
	v_mul_f32_e32 v223, 0xbfb8aa3b, v223
	v_mul_f32_e32 v224, 0xbfb8aa3b, v224
	v_mul_f32_e32 v225, 0xbfb8aa3b, v225
	v_mul_f32_e32 v226, 0xbfb8aa3b, v226
	v_mul_f32_e32 v227, 0xbfb8aa3b, v227
	v_mul_f32_e32 v228, 0xbfb8aa3b, v228
	v_mul_f32_e32 v229, 0xbfb8aa3b, v229
	v_pk_fma_f32 v[0:1], v[0:1], v[172:173], v[198:199] op_sel_hi:[1,0,1]
	v_pk_fma_f32 v[2:3], v[2:3], v[172:173], v[200:201] op_sel_hi:[1,0,1]
	v_pk_fma_f32 v[4:5], v[4:5], v[172:173], v[202:203] op_sel_hi:[1,0,1]
	v_pk_fma_f32 v[6:7], v[6:7], v[172:173], v[204:205] op_sel_hi:[1,0,1]
	v_pk_fma_f32 v[8:9], v[8:9], v[172:173], v[206:207] op_sel_hi:[1,0,1]
	v_pk_fma_f32 v[10:11], v[10:11], v[172:173], v[208:209] op_sel_hi:[1,0,1]
	v_pk_fma_f32 v[12:13], v[12:13], v[172:173], v[210:211] op_sel_hi:[1,0,1]
	v_pk_fma_f32 v[14:15], v[14:15], v[172:173], v[212:213] op_sel_hi:[1,0,1]
	v_pk_fma_f32 v[16:17], v[16:17], v[172:173], v[214:215] op_sel_hi:[1,0,1]
	v_pk_fma_f32 v[18:19], v[18:19], v[172:173], v[216:217] op_sel_hi:[1,0,1]
	v_pk_fma_f32 v[20:21], v[20:21], v[172:173], v[218:219] op_sel_hi:[1,0,1]
	v_pk_fma_f32 v[22:23], v[22:23], v[172:173], v[220:221] op_sel_hi:[1,0,1]
	v_pk_fma_f32 v[24:25], v[24:25], v[172:173], v[222:223] op_sel_hi:[1,0,1]
	v_pk_fma_f32 v[26:27], v[26:27], v[172:173], v[224:225] op_sel_hi:[1,0,1]
	v_pk_fma_f32 v[28:29], v[28:29], v[172:173], v[226:227] op_sel_hi:[1,0,1]
	v_pk_fma_f32 v[30:31], v[30:31], v[172:173], v[228:229] op_sel_hi:[1,0,1]
	v_exp_f32_e32 v0, v0
	v_exp_f32_e32 v1, v1
	v_exp_f32_e32 v2, v2
	v_exp_f32_e32 v3, v3
	v_exp_f32_e32 v4, v4
	v_exp_f32_e32 v5, v5
	v_exp_f32_e32 v6, v6
	v_exp_f32_e32 v7, v7
	v_exp_f32_e32 v8, v8
	v_exp_f32_e32 v9, v9
	v_exp_f32_e32 v10, v10
	v_exp_f32_e32 v11, v11
	v_exp_f32_e32 v12, v12
	v_exp_f32_e32 v13, v13
	v_exp_f32_e32 v14, v14
	v_exp_f32_e32 v15, v15
	v_exp_f32_e32 v16, v16
	v_exp_f32_e32 v17, v17
	v_exp_f32_e32 v18, v18
	v_exp_f32_e32 v19, v19
	v_exp_f32_e32 v20, v20
	v_exp_f32_e32 v21, v21
	v_exp_f32_e32 v22, v22
	v_exp_f32_e32 v23, v23
	v_exp_f32_e32 v24, v24
	v_exp_f32_e32 v25, v25
	v_exp_f32_e32 v26, v26
	v_exp_f32_e32 v27, v27
	v_exp_f32_e32 v28, v28
	v_exp_f32_e32 v29, v29
	v_exp_f32_e32 v30, v30
	v_exp_f32_e32 v31, v31
	v_pk_add_f32 v[0:1], v[0:1], 1.0 op_sel_hi:[1,0]
	v_pk_add_f32 v[2:3], v[2:3], 1.0 op_sel_hi:[1,0]
	v_pk_add_f32 v[4:5], v[4:5], 1.0 op_sel_hi:[1,0]
	v_pk_add_f32 v[6:7], v[6:7], 1.0 op_sel_hi:[1,0]
	v_pk_add_f32 v[8:9], v[8:9], 1.0 op_sel_hi:[1,0]
	v_pk_add_f32 v[10:11], v[10:11], 1.0 op_sel_hi:[1,0]
	v_pk_add_f32 v[12:13], v[12:13], 1.0 op_sel_hi:[1,0]
	v_pk_add_f32 v[14:15], v[14:15], 1.0 op_sel_hi:[1,0]
	v_pk_add_f32 v[16:17], v[16:17], 1.0 op_sel_hi:[1,0]
	v_pk_add_f32 v[18:19], v[18:19], 1.0 op_sel_hi:[1,0]
	v_pk_add_f32 v[20:21], v[20:21], 1.0 op_sel_hi:[1,0]
	v_pk_add_f32 v[22:23], v[22:23], 1.0 op_sel_hi:[1,0]
	v_pk_add_f32 v[24:25], v[24:25], 1.0 op_sel_hi:[1,0]
	v_pk_add_f32 v[26:27], v[26:27], 1.0 op_sel_hi:[1,0]
	v_pk_add_f32 v[28:29], v[28:29], 1.0 op_sel_hi:[1,0]
	v_pk_add_f32 v[30:31], v[30:31], 1.0 op_sel_hi:[1,0]
	v_rcp_f32_e32 v0, v0
	v_rcp_f32_e32 v1, v1
	v_rcp_f32_e32 v2, v2
	v_rcp_f32_e32 v3, v3
	v_rcp_f32_e32 v4, v4
	v_rcp_f32_e32 v5, v5
	v_rcp_f32_e32 v6, v6
	v_rcp_f32_e32 v7, v7
	v_rcp_f32_e32 v8, v8
	v_rcp_f32_e32 v9, v9
	v_rcp_f32_e32 v10, v10
	v_rcp_f32_e32 v11, v11
	v_rcp_f32_e32 v12, v12
	v_rcp_f32_e32 v13, v13
	v_rcp_f32_e32 v14, v14
	v_rcp_f32_e32 v15, v15
	v_rcp_f32_e32 v16, v16
	v_rcp_f32_e32 v17, v17
	v_rcp_f32_e32 v18, v18
	v_rcp_f32_e32 v19, v19
	v_rcp_f32_e32 v20, v20
	v_rcp_f32_e32 v21, v21
	v_rcp_f32_e32 v22, v22
	v_rcp_f32_e32 v23, v23
	v_rcp_f32_e32 v24, v24
	v_rcp_f32_e32 v25, v25
	v_rcp_f32_e32 v26, v26
	v_rcp_f32_e32 v27, v27
	v_rcp_f32_e32 v28, v28
	v_rcp_f32_e32 v29, v29
	v_rcp_f32_e32 v30, v30
	v_rcp_f32_e32 v31, v31
	s_nop 0
	v_cvt_pk_bf16_f32 v0, v0, v1
	v_cvt_pk_bf16_f32 v1, v2, v3
	v_cvt_pk_bf16_f32 v2, v4, v5
	v_cvt_pk_bf16_f32 v3, v6, v7
	v_cvt_pk_bf16_f32 v4, v8, v9
	v_cvt_pk_bf16_f32 v5, v10, v11
	v_cvt_pk_bf16_f32 v6, v12, v13
	v_cvt_pk_bf16_f32 v7, v14, v15
	v_cvt_pk_bf16_f32 v16, v16, v17
	v_cvt_pk_bf16_f32 v17, v18, v19
	v_cvt_pk_bf16_f32 v18, v20, v21
	v_cvt_pk_bf16_f32 v19, v22, v23
	v_cvt_pk_bf16_f32 v20, v24, v25
	v_cvt_pk_bf16_f32 v21, v26, v27
	v_cvt_pk_bf16_f32 v22, v28, v29
	v_cvt_pk_bf16_f32 v23, v30, v31
	v_permlane32_swap_b32_e32 v0, v2
	v_permlane32_swap_b32_e32 v1, v3
	v_permlane32_swap_b32_e32 v4, v6
	v_permlane32_swap_b32_e32 v5, v7
	v_permlane32_swap_b32_e32 v16, v18
	v_permlane32_swap_b32_e32 v17, v19
	v_permlane32_swap_b32_e32 v20, v22
	v_permlane32_swap_b32_e32 v21, v23
	global_store_dwordx4 v181, v[0:3], s[74:75] offset:0
	global_store_dwordx4 v181, v[4:7], s[74:75] offset:32
	global_store_dwordx4 v181, v[16:19], s[74:75] offset:64
	global_store_dwordx4 v181, v[20:23], s[74:75] offset:96
	s_add_u32 s74, s74, 0x44000
	s_addc_u32 s75, s75, 0
	v_pk_fma_f32 v[32:33], v[32:33], v[172:173], v[198:199] op_sel:[0,1,0] op_sel_hi:[1,1,1]
	v_pk_fma_f32 v[34:35], v[34:35], v[172:173], v[200:201] op_sel:[0,1,0] op_sel_hi:[1,1,1]
	v_pk_fma_f32 v[36:37], v[36:37], v[172:173], v[202:203] op_sel:[0,1,0] op_sel_hi:[1,1,1]
	v_pk_fma_f32 v[38:39], v[38:39], v[172:173], v[204:205] op_sel:[0,1,0] op_sel_hi:[1,1,1]
	v_pk_fma_f32 v[40:41], v[40:41], v[172:173], v[206:207] op_sel:[0,1,0] op_sel_hi:[1,1,1]
	v_pk_fma_f32 v[42:43], v[42:43], v[172:173], v[208:209] op_sel:[0,1,0] op_sel_hi:[1,1,1]
	v_pk_fma_f32 v[44:45], v[44:45], v[172:173], v[210:211] op_sel:[0,1,0] op_sel_hi:[1,1,1]
	v_pk_fma_f32 v[46:47], v[46:47], v[172:173], v[212:213] op_sel:[0,1,0] op_sel_hi:[1,1,1]
	v_pk_fma_f32 v[48:49], v[48:49], v[172:173], v[214:215] op_sel:[0,1,0] op_sel_hi:[1,1,1]
	v_pk_fma_f32 v[50:51], v[50:51], v[172:173], v[216:217] op_sel:[0,1,0] op_sel_hi:[1,1,1]
	v_pk_fma_f32 v[52:53], v[52:53], v[172:173], v[218:219] op_sel:[0,1,0] op_sel_hi:[1,1,1]
	v_pk_fma_f32 v[54:55], v[54:55], v[172:173], v[220:221] op_sel:[0,1,0] op_sel_hi:[1,1,1]
	v_pk_fma_f32 v[56:57], v[56:57], v[172:173], v[222:223] op_sel:[0,1,0] op_sel_hi:[1,1,1]
	v_pk_fma_f32 v[58:59], v[58:59], v[172:173], v[224:225] op_sel:[0,1,0] op_sel_hi:[1,1,1]
	v_pk_fma_f32 v[60:61], v[60:61], v[172:173], v[226:227] op_sel:[0,1,0] op_sel_hi:[1,1,1]
	v_pk_fma_f32 v[62:63], v[62:63], v[172:173], v[228:229] op_sel:[0,1,0] op_sel_hi:[1,1,1]
	v_exp_f32_e32 v32, v32
	v_exp_f32_e32 v33, v33
	v_exp_f32_e32 v34, v34
	v_exp_f32_e32 v35, v35
	v_exp_f32_e32 v36, v36
	v_exp_f32_e32 v37, v37
	v_exp_f32_e32 v38, v38
	v_exp_f32_e32 v39, v39
	v_exp_f32_e32 v40, v40
	v_exp_f32_e32 v41, v41
	v_exp_f32_e32 v42, v42
	v_exp_f32_e32 v43, v43
	v_exp_f32_e32 v44, v44
	v_exp_f32_e32 v45, v45
	v_exp_f32_e32 v46, v46
	v_exp_f32_e32 v47, v47
	v_exp_f32_e32 v48, v48
	v_exp_f32_e32 v49, v49
	v_exp_f32_e32 v50, v50
	v_exp_f32_e32 v51, v51
	v_exp_f32_e32 v52, v52
	v_exp_f32_e32 v53, v53
	v_exp_f32_e32 v54, v54
	v_exp_f32_e32 v55, v55
	v_exp_f32_e32 v56, v56
	v_exp_f32_e32 v57, v57
	v_exp_f32_e32 v58, v58
	v_exp_f32_e32 v59, v59
	v_exp_f32_e32 v60, v60
	v_exp_f32_e32 v61, v61
	v_exp_f32_e32 v62, v62
	v_exp_f32_e32 v63, v63
	v_pk_add_f32 v[32:33], v[32:33], 1.0 op_sel_hi:[1,0]
	v_pk_add_f32 v[34:35], v[34:35], 1.0 op_sel_hi:[1,0]
	v_pk_add_f32 v[36:37], v[36:37], 1.0 op_sel_hi:[1,0]
	v_pk_add_f32 v[38:39], v[38:39], 1.0 op_sel_hi:[1,0]
	v_pk_add_f32 v[40:41], v[40:41], 1.0 op_sel_hi:[1,0]
	v_pk_add_f32 v[42:43], v[42:43], 1.0 op_sel_hi:[1,0]
	v_pk_add_f32 v[44:45], v[44:45], 1.0 op_sel_hi:[1,0]
	v_pk_add_f32 v[46:47], v[46:47], 1.0 op_sel_hi:[1,0]
	v_pk_add_f32 v[48:49], v[48:49], 1.0 op_sel_hi:[1,0]
	v_pk_add_f32 v[50:51], v[50:51], 1.0 op_sel_hi:[1,0]
	v_pk_add_f32 v[52:53], v[52:53], 1.0 op_sel_hi:[1,0]
	v_pk_add_f32 v[54:55], v[54:55], 1.0 op_sel_hi:[1,0]
	v_pk_add_f32 v[56:57], v[56:57], 1.0 op_sel_hi:[1,0]
	v_pk_add_f32 v[58:59], v[58:59], 1.0 op_sel_hi:[1,0]
	v_pk_add_f32 v[60:61], v[60:61], 1.0 op_sel_hi:[1,0]
	v_pk_add_f32 v[62:63], v[62:63], 1.0 op_sel_hi:[1,0]
	v_rcp_f32_e32 v32, v32
	v_rcp_f32_e32 v33, v33
	v_rcp_f32_e32 v34, v34
	v_rcp_f32_e32 v35, v35
	v_rcp_f32_e32 v36, v36
	v_rcp_f32_e32 v37, v37
	v_rcp_f32_e32 v38, v38
	v_rcp_f32_e32 v39, v39
	v_rcp_f32_e32 v40, v40
	v_rcp_f32_e32 v41, v41
	v_rcp_f32_e32 v42, v42
	v_rcp_f32_e32 v43, v43
	v_rcp_f32_e32 v44, v44
	v_rcp_f32_e32 v45, v45
	v_rcp_f32_e32 v46, v46
	v_rcp_f32_e32 v47, v47
	v_rcp_f32_e32 v48, v48
	v_rcp_f32_e32 v49, v49
	v_rcp_f32_e32 v50, v50
	v_rcp_f32_e32 v51, v51
	v_rcp_f32_e32 v52, v52
	v_rcp_f32_e32 v53, v53
	v_rcp_f32_e32 v54, v54
	v_rcp_f32_e32 v55, v55
	v_rcp_f32_e32 v56, v56
	v_rcp_f32_e32 v57, v57
	v_rcp_f32_e32 v58, v58
	v_rcp_f32_e32 v59, v59
	v_rcp_f32_e32 v60, v60
	v_rcp_f32_e32 v61, v61
	v_rcp_f32_e32 v62, v62
	v_rcp_f32_e32 v63, v63
	s_nop 0
	v_cvt_pk_bf16_f32 v32, v32, v33
	v_cvt_pk_bf16_f32 v33, v34, v35
	v_cvt_pk_bf16_f32 v34, v36, v37
	v_cvt_pk_bf16_f32 v35, v38, v39
	v_cvt_pk_bf16_f32 v36, v40, v41
	v_cvt_pk_bf16_f32 v37, v42, v43
	v_cvt_pk_bf16_f32 v38, v44, v45
	v_cvt_pk_bf16_f32 v39, v46, v47
	v_cvt_pk_bf16_f32 v48, v48, v49
	v_cvt_pk_bf16_f32 v49, v50, v51
	v_cvt_pk_bf16_f32 v50, v52, v53
	v_cvt_pk_bf16_f32 v51, v54, v55
	v_cvt_pk_bf16_f32 v52, v56, v57
	v_cvt_pk_bf16_f32 v53, v58, v59
	v_cvt_pk_bf16_f32 v54, v60, v61
	v_cvt_pk_bf16_f32 v55, v62, v63
	v_permlane32_swap_b32_e32 v32, v34
	v_permlane32_swap_b32_e32 v33, v35
	v_permlane32_swap_b32_e32 v36, v38
	v_permlane32_swap_b32_e32 v37, v39
	v_permlane32_swap_b32_e32 v48, v50
	v_permlane32_swap_b32_e32 v49, v51
	v_permlane32_swap_b32_e32 v52, v54
	v_permlane32_swap_b32_e32 v53, v55
	global_store_dwordx4 v181, v[32:35], s[74:75] offset:0
	global_store_dwordx4 v181, v[36:39], s[74:75] offset:32
	global_store_dwordx4 v181, v[48:51], s[74:75] offset:64
	global_store_dwordx4 v181, v[52:55], s[74:75] offset:96
	s_add_u32 s74, s74, 0x44000
	s_addc_u32 s75, s75, 0
	v_pk_fma_f32 v[64:65], v[64:65], v[174:175], v[198:199] op_sel_hi:[1,0,1]
	v_pk_fma_f32 v[66:67], v[66:67], v[174:175], v[200:201] op_sel_hi:[1,0,1]
	v_pk_fma_f32 v[68:69], v[68:69], v[174:175], v[202:203] op_sel_hi:[1,0,1]
	v_pk_fma_f32 v[70:71], v[70:71], v[174:175], v[204:205] op_sel_hi:[1,0,1]
	v_pk_fma_f32 v[72:73], v[72:73], v[174:175], v[206:207] op_sel_hi:[1,0,1]
	v_pk_fma_f32 v[74:75], v[74:75], v[174:175], v[208:209] op_sel_hi:[1,0,1]
	v_pk_fma_f32 v[76:77], v[76:77], v[174:175], v[210:211] op_sel_hi:[1,0,1]
	v_pk_fma_f32 v[78:79], v[78:79], v[174:175], v[212:213] op_sel_hi:[1,0,1]
	v_pk_fma_f32 v[80:81], v[80:81], v[174:175], v[214:215] op_sel_hi:[1,0,1]
	v_pk_fma_f32 v[82:83], v[82:83], v[174:175], v[216:217] op_sel_hi:[1,0,1]
	v_pk_fma_f32 v[84:85], v[84:85], v[174:175], v[218:219] op_sel_hi:[1,0,1]
	v_pk_fma_f32 v[86:87], v[86:87], v[174:175], v[220:221] op_sel_hi:[1,0,1]
	v_pk_fma_f32 v[88:89], v[88:89], v[174:175], v[222:223] op_sel_hi:[1,0,1]
	v_pk_fma_f32 v[90:91], v[90:91], v[174:175], v[224:225] op_sel_hi:[1,0,1]
	v_pk_fma_f32 v[92:93], v[92:93], v[174:175], v[226:227] op_sel_hi:[1,0,1]
	v_pk_fma_f32 v[94:95], v[94:95], v[174:175], v[228:229] op_sel_hi:[1,0,1]
	v_exp_f32_e32 v64, v64
	v_exp_f32_e32 v65, v65
	v_exp_f32_e32 v66, v66
	v_exp_f32_e32 v67, v67
	v_exp_f32_e32 v68, v68
	v_exp_f32_e32 v69, v69
	v_exp_f32_e32 v70, v70
	v_exp_f32_e32 v71, v71
	v_exp_f32_e32 v72, v72
	v_exp_f32_e32 v73, v73
	v_exp_f32_e32 v74, v74
	v_exp_f32_e32 v75, v75
	v_exp_f32_e32 v76, v76
	v_exp_f32_e32 v77, v77
	v_exp_f32_e32 v78, v78
	v_exp_f32_e32 v79, v79
	v_exp_f32_e32 v80, v80
	v_exp_f32_e32 v81, v81
	v_exp_f32_e32 v82, v82
	v_exp_f32_e32 v83, v83
	v_exp_f32_e32 v84, v84
	v_exp_f32_e32 v85, v85
	v_exp_f32_e32 v86, v86
	v_exp_f32_e32 v87, v87
	v_exp_f32_e32 v88, v88
	v_exp_f32_e32 v89, v89
	v_exp_f32_e32 v90, v90
	v_exp_f32_e32 v91, v91
	v_exp_f32_e32 v92, v92
	v_exp_f32_e32 v93, v93
	v_exp_f32_e32 v94, v94
	v_exp_f32_e32 v95, v95
	v_pk_add_f32 v[64:65], v[64:65], 1.0 op_sel_hi:[1,0]
	v_pk_add_f32 v[66:67], v[66:67], 1.0 op_sel_hi:[1,0]
	v_pk_add_f32 v[68:69], v[68:69], 1.0 op_sel_hi:[1,0]
	v_pk_add_f32 v[70:71], v[70:71], 1.0 op_sel_hi:[1,0]
	v_pk_add_f32 v[72:73], v[72:73], 1.0 op_sel_hi:[1,0]
	v_pk_add_f32 v[74:75], v[74:75], 1.0 op_sel_hi:[1,0]
	v_pk_add_f32 v[76:77], v[76:77], 1.0 op_sel_hi:[1,0]
	v_pk_add_f32 v[78:79], v[78:79], 1.0 op_sel_hi:[1,0]
	v_pk_add_f32 v[80:81], v[80:81], 1.0 op_sel_hi:[1,0]
	v_pk_add_f32 v[82:83], v[82:83], 1.0 op_sel_hi:[1,0]
	v_pk_add_f32 v[84:85], v[84:85], 1.0 op_sel_hi:[1,0]
	v_pk_add_f32 v[86:87], v[86:87], 1.0 op_sel_hi:[1,0]
	v_pk_add_f32 v[88:89], v[88:89], 1.0 op_sel_hi:[1,0]
	v_pk_add_f32 v[90:91], v[90:91], 1.0 op_sel_hi:[1,0]
	v_pk_add_f32 v[92:93], v[92:93], 1.0 op_sel_hi:[1,0]
	v_pk_add_f32 v[94:95], v[94:95], 1.0 op_sel_hi:[1,0]
	v_rcp_f32_e32 v64, v64
	v_rcp_f32_e32 v65, v65
	v_rcp_f32_e32 v66, v66
	v_rcp_f32_e32 v67, v67
	v_rcp_f32_e32 v68, v68
	v_rcp_f32_e32 v69, v69
	v_rcp_f32_e32 v70, v70
	v_rcp_f32_e32 v71, v71
	v_rcp_f32_e32 v72, v72
	v_rcp_f32_e32 v73, v73
	v_rcp_f32_e32 v74, v74
	v_rcp_f32_e32 v75, v75
	v_rcp_f32_e32 v76, v76
	v_rcp_f32_e32 v77, v77
	v_rcp_f32_e32 v78, v78
	v_rcp_f32_e32 v79, v79
	v_rcp_f32_e32 v80, v80
	v_rcp_f32_e32 v81, v81
	v_rcp_f32_e32 v82, v82
	v_rcp_f32_e32 v83, v83
	v_rcp_f32_e32 v84, v84
	v_rcp_f32_e32 v85, v85
	v_rcp_f32_e32 v86, v86
	v_rcp_f32_e32 v87, v87
	v_rcp_f32_e32 v88, v88
	v_rcp_f32_e32 v89, v89
	v_rcp_f32_e32 v90, v90
	v_rcp_f32_e32 v91, v91
	v_rcp_f32_e32 v92, v92
	v_rcp_f32_e32 v93, v93
	v_rcp_f32_e32 v94, v94
	v_rcp_f32_e32 v95, v95
	s_nop 0
	v_cvt_pk_bf16_f32 v64, v64, v65
	v_cvt_pk_bf16_f32 v65, v66, v67
	v_cvt_pk_bf16_f32 v66, v68, v69
	v_cvt_pk_bf16_f32 v67, v70, v71
	v_cvt_pk_bf16_f32 v68, v72, v73
	v_cvt_pk_bf16_f32 v69, v74, v75
	v_cvt_pk_bf16_f32 v70, v76, v77
	v_cvt_pk_bf16_f32 v71, v78, v79
	v_cvt_pk_bf16_f32 v80, v80, v81
	v_cvt_pk_bf16_f32 v81, v82, v83
	v_cvt_pk_bf16_f32 v82, v84, v85
	v_cvt_pk_bf16_f32 v83, v86, v87
	v_cvt_pk_bf16_f32 v84, v88, v89
	v_cvt_pk_bf16_f32 v85, v90, v91
	v_cvt_pk_bf16_f32 v86, v92, v93
	v_cvt_pk_bf16_f32 v87, v94, v95
	v_permlane32_swap_b32_e32 v64, v66
	v_permlane32_swap_b32_e32 v65, v67
	v_permlane32_swap_b32_e32 v68, v70
	v_permlane32_swap_b32_e32 v69, v71
	v_permlane32_swap_b32_e32 v80, v82
	v_permlane32_swap_b32_e32 v81, v83
	v_permlane32_swap_b32_e32 v84, v86
	v_permlane32_swap_b32_e32 v85, v87
	global_store_dwordx4 v181, v[64:67], s[74:75] offset:0
	global_store_dwordx4 v181, v[68:71], s[74:75] offset:32
	global_store_dwordx4 v181, v[80:83], s[74:75] offset:64
	global_store_dwordx4 v181, v[84:87], s[74:75] offset:96
	s_add_u32 s74, s74, 0x44000
	s_addc_u32 s75, s75, 0
	v_pk_fma_f32 v[96:97], v[96:97], v[174:175], v[198:199] op_sel:[0,1,0] op_sel_hi:[1,1,1]
	v_pk_fma_f32 v[98:99], v[98:99], v[174:175], v[200:201] op_sel:[0,1,0] op_sel_hi:[1,1,1]
	v_pk_fma_f32 v[100:101], v[100:101], v[174:175], v[202:203] op_sel:[0,1,0] op_sel_hi:[1,1,1]
	v_pk_fma_f32 v[102:103], v[102:103], v[174:175], v[204:205] op_sel:[0,1,0] op_sel_hi:[1,1,1]
	v_pk_fma_f32 v[104:105], v[104:105], v[174:175], v[206:207] op_sel:[0,1,0] op_sel_hi:[1,1,1]
	v_pk_fma_f32 v[106:107], v[106:107], v[174:175], v[208:209] op_sel:[0,1,0] op_sel_hi:[1,1,1]
	v_pk_fma_f32 v[108:109], v[108:109], v[174:175], v[210:211] op_sel:[0,1,0] op_sel_hi:[1,1,1]
	v_pk_fma_f32 v[110:111], v[110:111], v[174:175], v[212:213] op_sel:[0,1,0] op_sel_hi:[1,1,1]
	v_pk_fma_f32 v[112:113], v[112:113], v[174:175], v[214:215] op_sel:[0,1,0] op_sel_hi:[1,1,1]
	v_pk_fma_f32 v[114:115], v[114:115], v[174:175], v[216:217] op_sel:[0,1,0] op_sel_hi:[1,1,1]
	v_pk_fma_f32 v[116:117], v[116:117], v[174:175], v[218:219] op_sel:[0,1,0] op_sel_hi:[1,1,1]
	v_pk_fma_f32 v[118:119], v[118:119], v[174:175], v[220:221] op_sel:[0,1,0] op_sel_hi:[1,1,1]
	v_pk_fma_f32 v[120:121], v[120:121], v[174:175], v[222:223] op_sel:[0,1,0] op_sel_hi:[1,1,1]
	v_pk_fma_f32 v[122:123], v[122:123], v[174:175], v[224:225] op_sel:[0,1,0] op_sel_hi:[1,1,1]
	v_pk_fma_f32 v[124:125], v[124:125], v[174:175], v[226:227] op_sel:[0,1,0] op_sel_hi:[1,1,1]
	v_pk_fma_f32 v[126:127], v[126:127], v[174:175], v[228:229] op_sel:[0,1,0] op_sel_hi:[1,1,1]
	v_exp_f32_e32 v96, v96
	v_exp_f32_e32 v97, v97
	v_exp_f32_e32 v98, v98
	v_exp_f32_e32 v99, v99
	v_exp_f32_e32 v100, v100
	v_exp_f32_e32 v101, v101
	v_exp_f32_e32 v102, v102
	v_exp_f32_e32 v103, v103
	v_exp_f32_e32 v104, v104
	v_exp_f32_e32 v105, v105
	v_exp_f32_e32 v106, v106
	v_exp_f32_e32 v107, v107
	v_exp_f32_e32 v108, v108
	v_exp_f32_e32 v109, v109
	v_exp_f32_e32 v110, v110
	v_exp_f32_e32 v111, v111
	v_exp_f32_e32 v112, v112
	v_exp_f32_e32 v113, v113
	v_exp_f32_e32 v114, v114
	v_exp_f32_e32 v115, v115
	v_exp_f32_e32 v116, v116
	v_exp_f32_e32 v117, v117
	v_exp_f32_e32 v118, v118
	v_exp_f32_e32 v119, v119
	v_exp_f32_e32 v120, v120
	v_exp_f32_e32 v121, v121
	v_exp_f32_e32 v122, v122
	v_exp_f32_e32 v123, v123
	v_exp_f32_e32 v124, v124
	v_exp_f32_e32 v125, v125
	v_exp_f32_e32 v126, v126
	v_exp_f32_e32 v127, v127
	v_pk_add_f32 v[96:97], v[96:97], 1.0 op_sel_hi:[1,0]
	v_pk_add_f32 v[98:99], v[98:99], 1.0 op_sel_hi:[1,0]
	v_pk_add_f32 v[100:101], v[100:101], 1.0 op_sel_hi:[1,0]
	v_pk_add_f32 v[102:103], v[102:103], 1.0 op_sel_hi:[1,0]
	v_pk_add_f32 v[104:105], v[104:105], 1.0 op_sel_hi:[1,0]
	v_pk_add_f32 v[106:107], v[106:107], 1.0 op_sel_hi:[1,0]
	v_pk_add_f32 v[108:109], v[108:109], 1.0 op_sel_hi:[1,0]
	v_pk_add_f32 v[110:111], v[110:111], 1.0 op_sel_hi:[1,0]
	v_pk_add_f32 v[112:113], v[112:113], 1.0 op_sel_hi:[1,0]
	v_pk_add_f32 v[114:115], v[114:115], 1.0 op_sel_hi:[1,0]
	v_pk_add_f32 v[116:117], v[116:117], 1.0 op_sel_hi:[1,0]
	v_pk_add_f32 v[118:119], v[118:119], 1.0 op_sel_hi:[1,0]
	v_pk_add_f32 v[120:121], v[120:121], 1.0 op_sel_hi:[1,0]
	v_pk_add_f32 v[122:123], v[122:123], 1.0 op_sel_hi:[1,0]
	v_pk_add_f32 v[124:125], v[124:125], 1.0 op_sel_hi:[1,0]
	v_pk_add_f32 v[126:127], v[126:127], 1.0 op_sel_hi:[1,0]
	v_rcp_f32_e32 v96, v96
	v_rcp_f32_e32 v97, v97
	v_rcp_f32_e32 v98, v98
	v_rcp_f32_e32 v99, v99
	v_rcp_f32_e32 v100, v100
	v_rcp_f32_e32 v101, v101
	v_rcp_f32_e32 v102, v102
	v_rcp_f32_e32 v103, v103
	v_rcp_f32_e32 v104, v104
	v_rcp_f32_e32 v105, v105
	v_rcp_f32_e32 v106, v106
	v_rcp_f32_e32 v107, v107
	v_rcp_f32_e32 v108, v108
	v_rcp_f32_e32 v109, v109
	v_rcp_f32_e32 v110, v110
	v_rcp_f32_e32 v111, v111
	v_rcp_f32_e32 v112, v112
	v_rcp_f32_e32 v113, v113
	v_rcp_f32_e32 v114, v114
	v_rcp_f32_e32 v115, v115
	v_rcp_f32_e32 v116, v116
	v_rcp_f32_e32 v117, v117
	v_rcp_f32_e32 v118, v118
	v_rcp_f32_e32 v119, v119
	v_rcp_f32_e32 v120, v120
	v_rcp_f32_e32 v121, v121
	v_rcp_f32_e32 v122, v122
	v_rcp_f32_e32 v123, v123
	v_rcp_f32_e32 v124, v124
	v_rcp_f32_e32 v125, v125
	v_rcp_f32_e32 v126, v126
	v_rcp_f32_e32 v127, v127
	s_nop 0
	v_cvt_pk_bf16_f32 v96, v96, v97
	v_cvt_pk_bf16_f32 v97, v98, v99
	v_cvt_pk_bf16_f32 v98, v100, v101
	v_cvt_pk_bf16_f32 v99, v102, v103
	v_cvt_pk_bf16_f32 v100, v104, v105
	v_cvt_pk_bf16_f32 v101, v106, v107
	v_cvt_pk_bf16_f32 v102, v108, v109
	v_cvt_pk_bf16_f32 v103, v110, v111
	v_cvt_pk_bf16_f32 v112, v112, v113
	v_cvt_pk_bf16_f32 v113, v114, v115
	v_cvt_pk_bf16_f32 v114, v116, v117
	v_cvt_pk_bf16_f32 v115, v118, v119
	v_cvt_pk_bf16_f32 v116, v120, v121
	v_cvt_pk_bf16_f32 v117, v122, v123
	v_cvt_pk_bf16_f32 v118, v124, v125
	v_cvt_pk_bf16_f32 v119, v126, v127
	v_permlane32_swap_b32_e32 v96, v98
	v_permlane32_swap_b32_e32 v97, v99
	v_permlane32_swap_b32_e32 v100, v102
	v_permlane32_swap_b32_e32 v101, v103
	v_permlane32_swap_b32_e32 v112, v114
	v_permlane32_swap_b32_e32 v113, v115
	v_permlane32_swap_b32_e32 v116, v118
	v_permlane32_swap_b32_e32 v117, v119
	global_store_dwordx4 v181, v[96:99], s[74:75] offset:0
	global_store_dwordx4 v181, v[100:103], s[74:75] offset:32
	global_store_dwordx4 v181, v[112:115], s[74:75] offset:64
	global_store_dwordx4 v181, v[116:119], s[74:75] offset:96
	s_branch .Lpe_ret_L0
.Lpe_vt_L0:
	s_lshl_b32 s35, s34, 2
	s_add_u32 s35, s35, s28
	s_add_u32 s36, s28, 6
	s_cmp_eq_u32 s25, 8
	s_cselect_b32 s35, s36, s35
	s_lshr_b32 s36, s29, 11
	s_mul_i32 s36, s36, 10
	s_add_u32 s36, s36, s35
	s_lshl_b32 s36, s36, 18
	s_and_b32 s37, s29, 0x7ff
	s_lshl_b32 s37, s37, 1
	s_add_u32 s36, s36, s37
	s_add_u32 s38, s72, 0x14920000
	s_addc_u32 s39, s73, 0
	s_add_u32 s38, s38, s36
	s_addc_u32 s39, s39, 0
	s_mul_i32 s36, s26, 10240
	s_add_u32 s36, s36, 0x10000
	v_lshlrev_b32_e32 v180, 1, v197
	v_mul_u32_u24_e32 v181, 36, v146
	v_add3_u32 v180, v180, v181, s36
	v_lshrrev_b32_e32 v181, 3, v179
	v_and_b32_e32 v146, 7, v179
	v_lshlrev_b32_e32 v146, 4, v146
	v_mul_u32_u24_e32 v198, 144, v181
	v_add3_u32 v198, v198, v146, s36
	v_lshl_add_u32 v199, v181, 12, v146
	s_add_u32 s76, s99, s90
	s_cmp_lt_u32 s76, 0x440
	s_cselect_b32 s80, 1, 0
	s_cselect_b32 s83, 0x200000, 0
	s_lshl_b32 s76, s24, 19
	s_lshl_b32 s77, s26, 16
	s_add_u32 s76, s76, s77
	s_and_b32 s77, s24, 7
	s_lshl_b32 s77, s77, 8
	s_add_u32 s76, s76, s77
	s_add_u32 s78, s72, 0xa120000
	s_addc_u32 s79, s73, 0
	s_add_u32 s78, s78, s76
	s_addc_u32 s79, s79, 0
	s_lshl_b32 s76, s25, 19
	s_add_u32 s76, s76, s83
	s_add_u32 s76, s76, s77
	s_lshl_b32 s77, s26, 16
	s_add_u32 s76, s76, s77
	s_add_u32 s82, s72, 0x0
	s_addc_u32 s83, s73, 0
	s_add_u32 s82, s82, s76
	s_addc_u32 s83, s83, 0
	s_lshl_b32 s76, s26, 12
	s_mov_b32 m0, s76
	s_nop 0
	global_load_lds_dwordx4 v145, s[78:79]
	s_add_u32 s78, s78, 0x4000
	s_addc_u32 s79, s79, 0
	s_add_u32 s76, s76, 0x400
	s_mov_b32 m0, s76
	s_nop 0
	global_load_lds_dwordx4 v185, s[78:79]
	s_add_u32 s78, s78, 0x4000
	s_addc_u32 s79, s79, 0
	s_add_u32 s76, s76, 0x400
	s_mov_b32 m0, s76
	s_nop 0
	global_load_lds_dwordx4 v145, s[78:79]
	s_add_u32 s78, s78, 0x4000
	s_addc_u32 s79, s79, 0
	s_add_u32 s76, s76, 0x400
	s_mov_b32 m0, s76
	s_nop 0
	global_load_lds_dwordx4 v185, s[78:79]
	s_add_u32 s78, s78, 0x4000
	s_addc_u32 s79, s79, 0
	s_add_u32 s76, s76, 0x400
	s_add_u32 s76, s76, 0x7000
	s_mov_b32 m0, s76
	s_nop 0
	global_load_lds_dwordx4 v145, s[82:83]
	s_add_u32 s82, s82, 0x4000
	s_addc_u32 s83, s83, 0
	s_add_u32 s76, s76, 0x400
	s_mov_b32 m0, s76
	s_nop 0
	global_load_lds_dwordx4 v185, s[82:83]
	s_add_u32 s82, s82, 0x4000
	s_addc_u32 s83, s83, 0
	s_add_u32 s76, s76, 0x400
	s_mov_b32 m0, s76
	s_nop 0
	global_load_lds_dwordx4 v145, s[82:83]
	s_add_u32 s82, s82, 0x4000
	s_addc_u32 s83, s83, 0
	s_add_u32 s76, s76, 0x400
	s_mov_b32 m0, s76
	s_nop 0
	global_load_lds_dwordx4 v185, s[82:83]
	s_add_u32 s82, s82, 0x4000
	s_addc_u32 s83, s83, 0
	s_add_u32 s76, s76, 0x400
	s_waitcnt vmcnt(8)
	v_mov_b32_e32 v197, 0x358637bd
	v_pk_add_f32 v[128:129], v[128:129], v[130:131]
	v_pk_add_f32 v[132:133], v[132:133], v[134:135]
	v_pk_add_f32 v[136:137], v[136:137], v[138:139]
	v_pk_add_f32 v[140:141], v[140:141], v[142:143]
	v_pk_add_f32 v[164:165], v[164:165], v[166:167]
	v_pk_add_f32 v[168:169], v[168:169], v[170:171]
	v_pk_add_f32 v[246:247], v[246:247], v[248:249]
	v_pk_add_f32 v[250:251], v[250:251], v[252:253]
	v_pk_add_f32 v[128:129], v[128:129], v[132:133]
	v_pk_add_f32 v[136:137], v[136:137], v[140:141]
	v_pk_add_f32 v[164:165], v[164:165], v[168:169]
	v_pk_add_f32 v[246:247], v[246:247], v[250:251]
	v_add_f32_e32 v128, v128, v129
	v_add_f32_e32 v136, v136, v137
	v_add_f32_e32 v164, v164, v165
	v_add_f32_e32 v246, v246, v247
	v_fmamk_f32 v128, v128, 0x3a800000, v197
	v_fmamk_f32 v136, v136, 0x3a800000, v197
	v_fmamk_f32 v164, v164, 0x3a800000, v197
	v_fmamk_f32 v246, v246, 0x3a800000, v197
	v_rsq_f32_e32 v172, v128
	v_rsq_f32_e32 v173, v136
	v_rsq_f32_e32 v174, v164
	v_rsq_f32_e32 v175, v246
	s_nop 0
	v_pk_mul_f32 v[0:1], v[0:1], v[172:173] op_sel_hi:[1,0]
	v_pk_mul_f32 v[2:3], v[2:3], v[172:173] op_sel_hi:[1,0]
	v_pk_mul_f32 v[4:5], v[4:5], v[172:173] op_sel_hi:[1,0]
	v_pk_mul_f32 v[6:7], v[6:7], v[172:173] op_sel_hi:[1,0]
	v_pk_mul_f32 v[8:9], v[8:9], v[172:173] op_sel_hi:[1,0]
	v_pk_mul_f32 v[10:11], v[10:11], v[172:173] op_sel_hi:[1,0]
	v_pk_mul_f32 v[12:13], v[12:13], v[172:173] op_sel_hi:[1,0]
	v_pk_mul_f32 v[14:15], v[14:15], v[172:173] op_sel_hi:[1,0]
	v_pk_mul_f32 v[16:17], v[16:17], v[172:173] op_sel_hi:[1,0]
	v_pk_mul_f32 v[18:19], v[18:19], v[172:173] op_sel_hi:[1,0]
	v_pk_mul_f32 v[20:21], v[20:21], v[172:173] op_sel_hi:[1,0]
	v_pk_mul_f32 v[22:23], v[22:23], v[172:173] op_sel_hi:[1,0]
	v_pk_mul_f32 v[24:25], v[24:25], v[172:173] op_sel_hi:[1,0]
	v_pk_mul_f32 v[26:27], v[26:27], v[172:173] op_sel_hi:[1,0]
	v_pk_mul_f32 v[28:29], v[28:29], v[172:173] op_sel_hi:[1,0]
	v_pk_mul_f32 v[30:31], v[30:31], v[172:173] op_sel_hi:[1,0]
	v_pk_mul_f32 v[32:33], v[32:33], v[172:173] op_sel:[0,1] op_sel_hi:[1,1]
	v_pk_mul_f32 v[34:35], v[34:35], v[172:173] op_sel:[0,1] op_sel_hi:[1,1]
	v_pk_mul_f32 v[36:37], v[36:37], v[172:173] op_sel:[0,1] op_sel_hi:[1,1]
	v_pk_mul_f32 v[38:39], v[38:39], v[172:173] op_sel:[0,1] op_sel_hi:[1,1]
	v_pk_mul_f32 v[40:41], v[40:41], v[172:173] op_sel:[0,1] op_sel_hi:[1,1]
	v_pk_mul_f32 v[42:43], v[42:43], v[172:173] op_sel:[0,1] op_sel_hi:[1,1]
	v_pk_mul_f32 v[44:45], v[44:45], v[172:173] op_sel:[0,1] op_sel_hi:[1,1]
	v_pk_mul_f32 v[46:47], v[46:47], v[172:173] op_sel:[0,1] op_sel_hi:[1,1]
	v_pk_mul_f32 v[48:49], v[48:49], v[172:173] op_sel:[0,1] op_sel_hi:[1,1]
	v_pk_mul_f32 v[50:51], v[50:51], v[172:173] op_sel:[0,1] op_sel_hi:[1,1]
	v_pk_mul_f32 v[52:53], v[52:53], v[172:173] op_sel:[0,1] op_sel_hi:[1,1]
	v_pk_mul_f32 v[54:55], v[54:55], v[172:173] op_sel:[0,1] op_sel_hi:[1,1]
	v_pk_mul_f32 v[56:57], v[56:57], v[172:173] op_sel:[0,1] op_sel_hi:[1,1]
	v_pk_mul_f32 v[58:59], v[58:59], v[172:173] op_sel:[0,1] op_sel_hi:[1,1]
	v_pk_mul_f32 v[60:61], v[60:61], v[172:173] op_sel:[0,1] op_sel_hi:[1,1]
	v_pk_mul_f32 v[62:63], v[62:63], v[172:173] op_sel:[0,1] op_sel_hi:[1,1]
	v_pk_mul_f32 v[64:65], v[64:65], v[174:175] op_sel_hi:[1,0]
	v_pk_mul_f32 v[66:67], v[66:67], v[174:175] op_sel_hi:[1,0]
	v_pk_mul_f32 v[68:69], v[68:69], v[174:175] op_sel_hi:[1,0]
	v_pk_mul_f32 v[70:71], v[70:71], v[174:175] op_sel_hi:[1,0]
	v_pk_mul_f32 v[72:73], v[72:73], v[174:175] op_sel_hi:[1,0]
	v_pk_mul_f32 v[74:75], v[74:75], v[174:175] op_sel_hi:[1,0]
	v_pk_mul_f32 v[76:77], v[76:77], v[174:175] op_sel_hi:[1,0]
	v_pk_mul_f32 v[78:79], v[78:79], v[174:175] op_sel_hi:[1,0]
	v_pk_mul_f32 v[80:81], v[80:81], v[174:175] op_sel_hi:[1,0]
	v_pk_mul_f32 v[82:83], v[82:83], v[174:175] op_sel_hi:[1,0]
	v_pk_mul_f32 v[84:85], v[84:85], v[174:175] op_sel_hi:[1,0]
	v_pk_mul_f32 v[86:87], v[86:87], v[174:175] op_sel_hi:[1,0]
	v_pk_mul_f32 v[88:89], v[88:89], v[174:175] op_sel_hi:[1,0]
	v_pk_mul_f32 v[90:91], v[90:91], v[174:175] op_sel_hi:[1,0]
	v_pk_mul_f32 v[92:93], v[92:93], v[174:175] op_sel_hi:[1,0]
	v_pk_mul_f32 v[94:95], v[94:95], v[174:175] op_sel_hi:[1,0]
	v_pk_mul_f32 v[96:97], v[96:97], v[174:175] op_sel:[0,1] op_sel_hi:[1,1]
	v_pk_mul_f32 v[98:99], v[98:99], v[174:175] op_sel:[0,1] op_sel_hi:[1,1]
	v_pk_mul_f32 v[100:101], v[100:101], v[174:175] op_sel:[0,1] op_sel_hi:[1,1]
	v_pk_mul_f32 v[102:103], v[102:103], v[174:175] op_sel:[0,1] op_sel_hi:[1,1]
	v_pk_mul_f32 v[104:105], v[104:105], v[174:175] op_sel:[0,1] op_sel_hi:[1,1]
	v_pk_mul_f32 v[106:107], v[106:107], v[174:175] op_sel:[0,1] op_sel_hi:[1,1]
	v_pk_mul_f32 v[108:109], v[108:109], v[174:175] op_sel:[0,1] op_sel_hi:[1,1]
	v_pk_mul_f32 v[110:111], v[110:111], v[174:175] op_sel:[0,1] op_sel_hi:[1,1]
	v_pk_mul_f32 v[112:113], v[112:113], v[174:175] op_sel:[0,1] op_sel_hi:[1,1]
	v_pk_mul_f32 v[114:115], v[114:115], v[174:175] op_sel:[0,1] op_sel_hi:[1,1]
	v_pk_mul_f32 v[116:117], v[116:117], v[174:175] op_sel:[0,1] op_sel_hi:[1,1]
	v_pk_mul_f32 v[118:119], v[118:119], v[174:175] op_sel:[0,1] op_sel_hi:[1,1]
	v_pk_mul_f32 v[120:121], v[120:121], v[174:175] op_sel:[0,1] op_sel_hi:[1,1]
	v_pk_mul_f32 v[122:123], v[122:123], v[174:175] op_sel:[0,1] op_sel_hi:[1,1]
	v_pk_mul_f32 v[124:125], v[124:125], v[174:175] op_sel:[0,1] op_sel_hi:[1,1]
	v_pk_mul_f32 v[126:127], v[126:127], v[174:175] op_sel:[0,1] op_sel_hi:[1,1]
	v_cvt_pk_bf16_f32 v0, v0, v1
	v_cvt_pk_bf16_f32 v1, v2, v3
	v_cvt_pk_bf16_f32 v2, v4, v5
	v_cvt_pk_bf16_f32 v3, v6, v7
	v_cvt_pk_bf16_f32 v4, v8, v9
	v_cvt_pk_bf16_f32 v5, v10, v11
	v_cvt_pk_bf16_f32 v6, v12, v13
	v_cvt_pk_bf16_f32 v7, v14, v15
	ds_write_b16 v180, v0 offset:0
	ds_write_b16_d16_hi v180, v0 offset:144
	ds_write_b16 v180, v1 offset:288
	ds_write_b16_d16_hi v180, v1 offset:432
	ds_write_b16 v180, v2 offset:1152
	ds_write_b16_d16_hi v180, v2 offset:1296
	ds_write_b16 v180, v3 offset:1440
	ds_write_b16_d16_hi v180, v3 offset:1584
	ds_write_b16 v180, v4 offset:2304
	ds_write_b16_d16_hi v180, v4 offset:2448
	ds_write_b16 v180, v5 offset:2592
	ds_write_b16_d16_hi v180, v5 offset:2736
	ds_write_b16 v180, v6 offset:3456
	ds_write_b16_d16_hi v180, v6 offset:3600
	ds_write_b16 v180, v7 offset:3744
	ds_write_b16_d16_hi v180, v7 offset:3888
	v_cvt_pk_bf16_f32 v16, v16, v17
	v_cvt_pk_bf16_f32 v17, v18, v19
	v_cvt_pk_bf16_f32 v18, v20, v21
	v_cvt_pk_bf16_f32 v19, v22, v23
	v_cvt_pk_bf16_f32 v20, v24, v25
	v_cvt_pk_bf16_f32 v21, v26, v27
	v_cvt_pk_bf16_f32 v22, v28, v29
	v_cvt_pk_bf16_f32 v23, v30, v31
	ds_write_b16 v180, v16 offset:4608
	ds_write_b16_d16_hi v180, v16 offset:4752
	ds_write_b16 v180, v17 offset:4896
	ds_write_b16_d16_hi v180, v17 offset:5040
	ds_write_b16 v180, v18 offset:5760
	ds_write_b16_d16_hi v180, v18 offset:5904
	ds_write_b16 v180, v19 offset:6048
	ds_write_b16_d16_hi v180, v19 offset:6192
	ds_write_b16 v180, v20 offset:6912
	ds_write_b16_d16_hi v180, v20 offset:7056
	ds_write_b16 v180, v21 offset:7200
	ds_write_b16_d16_hi v180, v21 offset:7344
	ds_write_b16 v180, v22 offset:8064
	ds_write_b16_d16_hi v180, v22 offset:8208
	ds_write_b16 v180, v23 offset:8352
	ds_write_b16_d16_hi v180, v23 offset:8496
	v_cvt_pk_bf16_f32 v32, v32, v33
	v_cvt_pk_bf16_f32 v33, v34, v35
	v_cvt_pk_bf16_f32 v34, v36, v37
	v_cvt_pk_bf16_f32 v35, v38, v39
	v_cvt_pk_bf16_f32 v36, v40, v41
	v_cvt_pk_bf16_f32 v37, v42, v43
	v_cvt_pk_bf16_f32 v38, v44, v45
	v_cvt_pk_bf16_f32 v39, v46, v47
	ds_write_b16 v180, v32 offset:64
	ds_write_b16_d16_hi v180, v32 offset:208
	ds_write_b16 v180, v33 offset:352
	ds_write_b16_d16_hi v180, v33 offset:496
	ds_write_b16 v180, v34 offset:1216
	ds_write_b16_d16_hi v180, v34 offset:1360
	ds_write_b16 v180, v35 offset:1504
	ds_write_b16_d16_hi v180, v35 offset:1648
	ds_write_b16 v180, v36 offset:2368
	ds_write_b16_d16_hi v180, v36 offset:2512
	ds_write_b16 v180, v37 offset:2656
	ds_write_b16_d16_hi v180, v37 offset:2800
	ds_write_b16 v180, v38 offset:3520
	ds_write_b16_d16_hi v180, v38 offset:3664
	ds_write_b16 v180, v39 offset:3808
	ds_write_b16_d16_hi v180, v39 offset:3952
	v_cvt_pk_bf16_f32 v48, v48, v49
	v_cvt_pk_bf16_f32 v49, v50, v51
	v_cvt_pk_bf16_f32 v50, v52, v53
	v_cvt_pk_bf16_f32 v51, v54, v55
	v_cvt_pk_bf16_f32 v52, v56, v57
	v_cvt_pk_bf16_f32 v53, v58, v59
	v_cvt_pk_bf16_f32 v54, v60, v61
	v_cvt_pk_bf16_f32 v55, v62, v63
	ds_write_b16 v180, v48 offset:4672
	ds_write_b16_d16_hi v180, v48 offset:4816
	ds_write_b16 v180, v49 offset:4960
	ds_write_b16_d16_hi v180, v49 offset:5104
	ds_write_b16 v180, v50 offset:5824
	ds_write_b16_d16_hi v180, v50 offset:5968
	ds_write_b16 v180, v51 offset:6112
	ds_write_b16_d16_hi v180, v51 offset:6256
	ds_write_b16 v180, v52 offset:6976
	ds_write_b16_d16_hi v180, v52 offset:7120
	ds_write_b16 v180, v53 offset:7264
	ds_write_b16_d16_hi v180, v53 offset:7408
	ds_write_b16 v180, v54 offset:8128
	ds_write_b16_d16_hi v180, v54 offset:8272
	ds_write_b16 v180, v55 offset:8416
	ds_write_b16_d16_hi v180, v55 offset:8560
	s_waitcnt lgkmcnt(0)
	ds_read_b128 v[0:3], v198 offset:0
	ds_read_b128 v[4:7], v198 offset:1152
	ds_read_b128 v[8:11], v198 offset:2304
	ds_read_b128 v[12:15], v198 offset:3456
	ds_read_b128 v[16:19], v198 offset:4608
	ds_read_b128 v[20:23], v198 offset:5760
	ds_read_b128 v[24:27], v198 offset:6912
	ds_read_b128 v[28:31], v198 offset:8064
	s_waitcnt lgkmcnt(7)
	global_store_dwordx4 v199, v[0:3], s[38:39]
	s_add_u32 s38, s38, 0x8000
	s_addc_u32 s39, s39, 0
	s_waitcnt lgkmcnt(6)
	global_store_dwordx4 v199, v[4:7], s[38:39]
	s_add_u32 s38, s38, 0x8000
	s_addc_u32 s39, s39, 0
	s_waitcnt lgkmcnt(5)
	global_store_dwordx4 v199, v[8:11], s[38:39]
	s_add_u32 s38, s38, 0x8000
	s_addc_u32 s39, s39, 0
	s_waitcnt lgkmcnt(4)
	global_store_dwordx4 v199, v[12:15], s[38:39]
	s_add_u32 s38, s38, 0x8000
	s_addc_u32 s39, s39, 0
	s_waitcnt lgkmcnt(3)
	global_store_dwordx4 v199, v[16:19], s[38:39]
	s_add_u32 s38, s38, 0x8000
	s_addc_u32 s39, s39, 0
	s_waitcnt lgkmcnt(2)
	global_store_dwordx4 v199, v[20:23], s[38:39]
	s_add_u32 s38, s38, 0x8000
	s_addc_u32 s39, s39, 0
	s_waitcnt lgkmcnt(1)
	global_store_dwordx4 v199, v[24:27], s[38:39]
	s_add_u32 s38, s38, 0x8000
	s_addc_u32 s39, s39, 0
	s_waitcnt lgkmcnt(0)
	global_store_dwordx4 v199, v[28:31], s[38:39]
	s_sub_u32 s38, s38, 229248
	s_subb_u32 s39, s39, 0
	v_cvt_pk_bf16_f32 v64, v64, v65
	v_cvt_pk_bf16_f32 v65, v66, v67
	v_cvt_pk_bf16_f32 v66, v68, v69
	v_cvt_pk_bf16_f32 v67, v70, v71
	v_cvt_pk_bf16_f32 v68, v72, v73
	v_cvt_pk_bf16_f32 v69, v74, v75
	v_cvt_pk_bf16_f32 v70, v76, v77
	v_cvt_pk_bf16_f32 v71, v78, v79
	ds_write_b16 v180, v64 offset:0
	ds_write_b16_d16_hi v180, v64 offset:144
	ds_write_b16 v180, v65 offset:288
	ds_write_b16_d16_hi v180, v65 offset:432
	ds_write_b16 v180, v66 offset:1152
	ds_write_b16_d16_hi v180, v66 offset:1296
	ds_write_b16 v180, v67 offset:1440
	ds_write_b16_d16_hi v180, v67 offset:1584
	ds_write_b16 v180, v68 offset:2304
	ds_write_b16_d16_hi v180, v68 offset:2448
	ds_write_b16 v180, v69 offset:2592
	ds_write_b16_d16_hi v180, v69 offset:2736
	ds_write_b16 v180, v70 offset:3456
	ds_write_b16_d16_hi v180, v70 offset:3600
	ds_write_b16 v180, v71 offset:3744
	ds_write_b16_d16_hi v180, v71 offset:3888
	v_cvt_pk_bf16_f32 v80, v80, v81
	v_cvt_pk_bf16_f32 v81, v82, v83
	v_cvt_pk_bf16_f32 v82, v84, v85
	v_cvt_pk_bf16_f32 v83, v86, v87
	v_cvt_pk_bf16_f32 v84, v88, v89
	v_cvt_pk_bf16_f32 v85, v90, v91
	v_cvt_pk_bf16_f32 v86, v92, v93
	v_cvt_pk_bf16_f32 v87, v94, v95
	ds_write_b16 v180, v80 offset:4608
	ds_write_b16_d16_hi v180, v80 offset:4752
	ds_write_b16 v180, v81 offset:4896
	ds_write_b16_d16_hi v180, v81 offset:5040
	ds_write_b16 v180, v82 offset:5760
	ds_write_b16_d16_hi v180, v82 offset:5904
	ds_write_b16 v180, v83 offset:6048
	ds_write_b16_d16_hi v180, v83 offset:6192
	ds_write_b16 v180, v84 offset:6912
	ds_write_b16_d16_hi v180, v84 offset:7056
	ds_write_b16 v180, v85 offset:7200
	ds_write_b16_d16_hi v180, v85 offset:7344
	ds_write_b16 v180, v86 offset:8064
	ds_write_b16_d16_hi v180, v86 offset:8208
	ds_write_b16 v180, v87 offset:8352
	ds_write_b16_d16_hi v180, v87 offset:8496
	v_cvt_pk_bf16_f32 v96, v96, v97
	v_cvt_pk_bf16_f32 v97, v98, v99
	v_cvt_pk_bf16_f32 v98, v100, v101
	v_cvt_pk_bf16_f32 v99, v102, v103
	v_cvt_pk_bf16_f32 v100, v104, v105
	v_cvt_pk_bf16_f32 v101, v106, v107
	v_cvt_pk_bf16_f32 v102, v108, v109
	v_cvt_pk_bf16_f32 v103, v110, v111
	ds_write_b16 v180, v96 offset:64
	ds_write_b16_d16_hi v180, v96 offset:208
	ds_write_b16 v180, v97 offset:352
	ds_write_b16_d16_hi v180, v97 offset:496
	ds_write_b16 v180, v98 offset:1216
	ds_write_b16_d16_hi v180, v98 offset:1360
	ds_write_b16 v180, v99 offset:1504
	ds_write_b16_d16_hi v180, v99 offset:1648
	ds_write_b16 v180, v100 offset:2368
	ds_write_b16_d16_hi v180, v100 offset:2512
	ds_write_b16 v180, v101 offset:2656
	ds_write_b16_d16_hi v180, v101 offset:2800
	ds_write_b16 v180, v102 offset:3520
	ds_write_b16_d16_hi v180, v102 offset:3664
	ds_write_b16 v180, v103 offset:3808
	ds_write_b16_d16_hi v180, v103 offset:3952
	v_cvt_pk_bf16_f32 v112, v112, v113
	v_cvt_pk_bf16_f32 v113, v114, v115
	v_cvt_pk_bf16_f32 v114, v116, v117
	v_cvt_pk_bf16_f32 v115, v118, v119
	v_cvt_pk_bf16_f32 v116, v120, v121
	v_cvt_pk_bf16_f32 v117, v122, v123
	v_cvt_pk_bf16_f32 v118, v124, v125
	v_cvt_pk_bf16_f32 v119, v126, v127
	ds_write_b16 v180, v112 offset:4672
	ds_write_b16_d16_hi v180, v112 offset:4816
	ds_write_b16 v180, v113 offset:4960
	ds_write_b16_d16_hi v180, v113 offset:5104
	ds_write_b16 v180, v114 offset:5824
	ds_write_b16_d16_hi v180, v114 offset:5968
	ds_write_b16 v180, v115 offset:6112
	ds_write_b16_d16_hi v180, v115 offset:6256
	ds_write_b16 v180, v116 offset:6976
	ds_write_b16_d16_hi v180, v116 offset:7120
	ds_write_b16 v180, v117 offset:7264
	ds_write_b16_d16_hi v180, v117 offset:7408
	ds_write_b16 v180, v118 offset:8128
	ds_write_b16_d16_hi v180, v118 offset:8272
	ds_write_b16 v180, v119 offset:8416
	ds_write_b16_d16_hi v180, v119 offset:8560
	s_waitcnt lgkmcnt(0)
	ds_read_b128 v[64:67], v198 offset:0
	ds_read_b128 v[68:71], v198 offset:1152
	ds_read_b128 v[72:75], v198 offset:2304
	ds_read_b128 v[76:79], v198 offset:3456
	ds_read_b128 v[80:83], v198 offset:4608
	ds_read_b128 v[84:87], v198 offset:5760
	ds_read_b128 v[88:91], v198 offset:6912
	ds_read_b128 v[92:95], v198 offset:8064
	s_waitcnt lgkmcnt(7)
	global_store_dwordx4 v199, v[64:67], s[38:39]
	s_add_u32 s38, s38, 0x8000
	s_addc_u32 s39, s39, 0
	s_waitcnt lgkmcnt(6)
	global_store_dwordx4 v199, v[68:71], s[38:39]
	s_add_u32 s38, s38, 0x8000
	s_addc_u32 s39, s39, 0
	s_waitcnt lgkmcnt(5)
	global_store_dwordx4 v199, v[72:75], s[38:39]
	s_add_u32 s38, s38, 0x8000
	s_addc_u32 s39, s39, 0
	s_waitcnt lgkmcnt(4)
	global_store_dwordx4 v199, v[76:79], s[38:39]
	s_add_u32 s38, s38, 0x8000
	s_addc_u32 s39, s39, 0
	s_waitcnt lgkmcnt(3)
	global_store_dwordx4 v199, v[80:83], s[38:39]
	s_add_u32 s38, s38, 0x8000
	s_addc_u32 s39, s39, 0
	s_waitcnt lgkmcnt(2)
	global_store_dwordx4 v199, v[84:87], s[38:39]
	s_add_u32 s38, s38, 0x8000
	s_addc_u32 s39, s39, 0
	s_waitcnt lgkmcnt(1)
	global_store_dwordx4 v199, v[88:91], s[38:39]
	s_add_u32 s38, s38, 0x8000
	s_addc_u32 s39, s39, 0
	s_waitcnt lgkmcnt(0)
	global_store_dwordx4 v199, v[92:95], s[38:39]

.Lpe_notv_L1:
	s_cmp_ge_u32 s25, 9
	s_cbranch_scc1 .Lpe_gates_L1
	s_lshr_b32 s34, s25, 1
	s_cmp_ge_u32 s25, 6
	s_cselect_b32 s35, 1, 0
	s_sub_u32 s34, s34, s35
	s_lshl_b32 s35, s98, 2
	s_add_u32 s35, s35, s34
	s_lshl_b32 s35, s35, 8
	v_readlane_b32 s82, v254, 14
	v_readlane_b32 s83, v254, 15
	s_add_u32 s82, s82, s35
	s_addc_u32 s83, s83, 0
	global_load_dwordx4 v[198:201], v146, s[82:83] offset:0
	global_load_dwordx4 v[202:205], v146, s[82:83] offset:32
	global_load_dwordx4 v[206:209], v146, s[82:83] offset:64
	global_load_dwordx4 v[210:213], v146, s[82:83] offset:96
	global_load_dwordx4 v[214:217], v146, s[82:83] offset:128
	global_load_dwordx4 v[218:221], v146, s[82:83] offset:160
	global_load_dwordx4 v[222:225], v146, s[82:83] offset:192
	global_load_dwordx4 v[226:229], v146, s[82:83] offset:224
	s_and_b32 s35, s34, 1
	s_cmp_eq_u32 s35, 0
	s_cselect_b32 s36, 0x3e000000, 1.0
	s_and_b32 s35, s29, 0x7ff
	s_lshl_b32 s35, s35, 7
	s_add_u32 s96, s72, 0x1ada0000
	s_addc_u32 s97, s73, 0
	s_add_u32 s96, s96, s35
	s_addc_u32 s97, s97, 0
	s_add_u32 s100, s96, 0x40000
	s_addc_u32 s101, s97, 0
	s_cmp_ge_u32 s34, 2
	s_cselect_b32 s37, 1, 0
	s_add_u32 s76, s99, s90
	s_cmp_lt_u32 s76, 0x440
	s_cselect_b32 s80, 1, 0
	s_cselect_b32 s83, 0x200000, 0
	s_lshl_b32 s76, s24, 19
	s_lshl_b32 s77, s26, 16
	s_add_u32 s76, s76, s77
	s_and_b32 s77, s24, 7
	s_lshl_b32 s77, s77, 8
	s_add_u32 s76, s76, s77
	s_add_u32 s78, s72, 0xa120000
	s_addc_u32 s79, s73, 0
	s_add_u32 s78, s78, s76
	s_addc_u32 s79, s79, 0
	s_lshl_b32 s76, s25, 19
	s_add_u32 s76, s76, s83
	s_add_u32 s76, s76, s77
	s_lshl_b32 s77, s26, 16
	s_add_u32 s76, s76, s77
	s_add_u32 s82, s72, 0x880000
	s_addc_u32 s83, s73, 0
	s_add_u32 s82, s82, s76
	s_addc_u32 s83, s83, 0
	s_lshl_b32 s76, s26, 12
	s_mov_b32 m0, s76
	s_nop 0
	global_load_lds_dwordx4 v177, s[78:79]
	s_add_u32 s78, s78, 0x4000
	s_addc_u32 s79, s79, 0
	s_add_u32 s76, s76, 0x400
	s_mov_b32 m0, s76
	s_nop 0
	global_load_lds_dwordx4 v185, s[78:79]
	s_add_u32 s78, s78, 0x4000
	s_addc_u32 s79, s79, 0
	s_add_u32 s76, s76, 0x400
	s_mov_b32 m0, s76
	s_nop 0
	global_load_lds_dwordx4 v177, s[78:79]
	s_add_u32 s78, s78, 0x4000
	s_addc_u32 s79, s79, 0
	s_add_u32 s76, s76, 0x400
	s_mov_b32 m0, s76
	s_nop 0
	global_load_lds_dwordx4 v185, s[78:79]
	s_add_u32 s78, s78, 0x4000
	s_addc_u32 s79, s79, 0
	s_add_u32 s76, s76, 0x400
	s_add_u32 s76, s76, 0x7000
	s_mov_b32 m0, s76
	s_nop 0
	global_load_lds_dwordx4 v177, s[82:83]
	s_add_u32 s82, s82, 0x4000
	s_addc_u32 s83, s83, 0
	s_add_u32 s76, s76, 0x400
	s_mov_b32 m0, s76
	s_nop 0
	global_load_lds_dwordx4 v185, s[82:83]
	s_add_u32 s82, s82, 0x4000
	s_addc_u32 s83, s83, 0
	s_add_u32 s76, s76, 0x400
	s_mov_b32 m0, s76
	s_nop 0
	global_load_lds_dwordx4 v177, s[82:83]
	s_add_u32 s82, s82, 0x4000
	s_addc_u32 s83, s83, 0
	s_add_u32 s76, s76, 0x400
	s_mov_b32 m0, s76
	s_nop 0
	global_load_lds_dwordx4 v185, s[82:83]
	s_add_u32 s82, s82, 0x4000
	s_addc_u32 s83, s83, 0
	s_add_u32 s76, s76, 0x400
	s_waitcnt vmcnt(16)
	v_lshlrev_b32_e32 v180, 7, v197
	v_add_u32_e32 v180, v180, v146
	v_mov_b32_e32 v197, 0x358637bd
	v_pk_add_f32 v[128:129], v[128:129], v[130:131]
	v_pk_add_f32 v[132:133], v[132:133], v[134:135]
	v_pk_add_f32 v[136:137], v[136:137], v[138:139]
	v_pk_add_f32 v[140:141], v[140:141], v[142:143]
	v_pk_add_f32 v[164:165], v[164:165], v[166:167]
	v_pk_add_f32 v[168:169], v[168:169], v[170:171]
	v_pk_add_f32 v[246:247], v[246:247], v[248:249]
	v_pk_add_f32 v[250:251], v[250:251], v[252:253]
	v_pk_add_f32 v[128:129], v[128:129], v[132:133]
	v_pk_add_f32 v[136:137], v[136:137], v[140:141]
	v_pk_add_f32 v[164:165], v[164:165], v[168:169]
	v_pk_add_f32 v[246:247], v[246:247], v[250:251]
	v_add_f32_e32 v128, v128, v129
	v_add_f32_e32 v136, v136, v137
	v_add_f32_e32 v164, v164, v165
	v_add_f32_e32 v246, v246, v247
	v_fmamk_f32 v128, v128, 0x3a800000, v197
	v_fmamk_f32 v136, v136, 0x3a800000, v197
	v_fmamk_f32 v164, v164, 0x3a800000, v197
	v_fmamk_f32 v246, v246, 0x3a800000, v197
	v_rsq_f32_e32 v172, v128
	v_rsq_f32_e32 v173, v136
	v_rsq_f32_e32 v174, v164
	v_rsq_f32_e32 v175, v246
	s_nop 0
	s_cmp_eq_u32 s37, 0
	s_cbranch_scc1 .Lpe_norope_ld_L1
	global_load_dwordx4 v[230:233], v180, s[96:97] offset:0
	global_load_dwordx4 v[234:237], v180, s[96:97] offset:32
	global_load_dwordx4 v[238:241], v180, s[96:97] offset:64
	global_load_dwordx4 v[242:245], v180, s[96:97] offset:96
	global_load_dwordx4 v[148:151], v180, s[100:101] offset:0
	global_load_dwordx4 v[152:155], v180, s[100:101] offset:32
	global_load_dwordx4 v[156:159], v180, s[100:101] offset:64
	global_load_dwordx4 v[160:163], v180, s[100:101] offset:96

.Lpe_gates_L1:
	s_lshl_b32 s35, s98, 11
	s_add_u32 s35, s35, s30
	s_sub_u32 s35, s35, 0x900
	s_lshl_b32 s35, s35, 2
	v_readlane_b32 s82, v254, 12
	v_readlane_b32 s83, v254, 13
	s_add_u32 s82, s82, s35
	s_addc_u32 s83, s83, 0
	global_load_dwordx4 v[198:201], v146, s[82:83] offset:0
	global_load_dwordx4 v[202:205], v146, s[82:83] offset:32
	global_load_dwordx4 v[206:209], v146, s[82:83] offset:64
	global_load_dwordx4 v[210:213], v146, s[82:83] offset:96
	global_load_dwordx4 v[214:217], v146, s[82:83] offset:128
	global_load_dwordx4 v[218:221], v146, s[82:83] offset:160
	global_load_dwordx4 v[222:225], v146, s[82:83] offset:192
	global_load_dwordx4 v[226:229], v146, s[82:83] offset:224
	s_add_u32 s76, s99, s90
	s_cmp_lt_u32 s76, 0x440
	s_cselect_b32 s80, 1, 0
	s_cselect_b32 s83, 0x200000, 0
	s_lshl_b32 s76, s24, 19
	s_lshl_b32 s77, s26, 16
	s_add_u32 s76, s76, s77
	s_and_b32 s77, s24, 7
	s_lshl_b32 s77, s77, 8
	s_add_u32 s76, s76, s77
	s_add_u32 s78, s72, 0xa120000
	s_addc_u32 s79, s73, 0
	s_add_u32 s78, s78, s76
	s_addc_u32 s79, s79, 0
	s_lshl_b32 s76, s25, 19
	s_add_u32 s76, s76, s83
	s_add_u32 s76, s76, s77
	s_lshl_b32 s77, s26, 16
	s_add_u32 s76, s76, s77
	s_add_u32 s82, s72, 0x880000
	s_addc_u32 s83, s73, 0
	s_add_u32 s82, s82, s76
	s_addc_u32 s83, s83, 0
	s_lshl_b32 s76, s26, 12
	s_mov_b32 m0, s76
	s_nop 0
	global_load_lds_dwordx4 v177, s[78:79]
	s_add_u32 s78, s78, 0x4000
	s_addc_u32 s79, s79, 0
	s_add_u32 s76, s76, 0x400
	s_mov_b32 m0, s76
	s_nop 0
	global_load_lds_dwordx4 v185, s[78:79]
	s_add_u32 s78, s78, 0x4000
	s_addc_u32 s79, s79, 0
	s_add_u32 s76, s76, 0x400
	s_mov_b32 m0, s76
	s_nop 0
	global_load_lds_dwordx4 v177, s[78:79]
	s_add_u32 s78, s78, 0x4000
	s_addc_u32 s79, s79, 0
	s_add_u32 s76, s76, 0x400
	s_mov_b32 m0, s76
	s_nop 0
	global_load_lds_dwordx4 v185, s[78:79]
	s_add_u32 s78, s78, 0x4000
	s_addc_u32 s79, s79, 0
	s_add_u32 s76, s76, 0x400
	s_add_u32 s76, s76, 0x7000
	s_mov_b32 m0, s76
	s_nop 0
	global_load_lds_dwordx4 v177, s[82:83]
	s_add_u32 s82, s82, 0x4000
	s_addc_u32 s83, s83, 0
	s_add_u32 s76, s76, 0x400
	s_mov_b32 m0, s76
	s_nop 0
	global_load_lds_dwordx4 v185, s[82:83]
	s_add_u32 s82, s82, 0x4000
	s_addc_u32 s83, s83, 0
	s_add_u32 s76, s76, 0x400
	s_mov_b32 m0, s76
	s_nop 0
	global_load_lds_dwordx4 v177, s[82:83]
	s_add_u32 s82, s82, 0x4000
	s_addc_u32 s83, s83, 0
	s_add_u32 s76, s76, 0x400
	s_mov_b32 m0, s76
	s_nop 0
	global_load_lds_dwordx4 v185, s[82:83]
	s_add_u32 s82, s82, 0x4000
	s_addc_u32 s83, s83, 0
	s_add_u32 s76, s76, 0x400
	s_waitcnt vmcnt(16)
	v_mov_b32_e32 v197, 0x358637bd
	v_pk_add_f32 v[128:129], v[128:129], v[130:131]
	v_pk_add_f32 v[132:133], v[132:133], v[134:135]
	v_pk_add_f32 v[136:137], v[136:137], v[138:139]
	v_pk_add_f32 v[140:141], v[140:141], v[142:143]
	v_pk_add_f32 v[164:165], v[164:165], v[166:167]
	v_pk_add_f32 v[168:169], v[168:169], v[170:171]
	v_pk_add_f32 v[246:247], v[246:247], v[248:249]
	v_pk_add_f32 v[250:251], v[250:251], v[252:253]
	v_pk_add_f32 v[128:129], v[128:129], v[132:133]
	v_pk_add_f32 v[136:137], v[136:137], v[140:141]
	v_pk_add_f32 v[164:165], v[164:165], v[168:169]
	v_pk_add_f32 v[246:247], v[246:247], v[250:251]
	v_add_f32_e32 v128, v128, v129
	v_add_f32_e32 v136, v136, v137
	v_add_f32_e32 v164, v164, v165
	v_add_f32_e32 v246, v246, v247
	v_fmamk_f32 v128, v128, 0x3a800000, v197
	v_fmamk_f32 v136, v136, 0x3a800000, v197
	v_fmamk_f32 v164, v164, 0x3a800000, v197
	v_fmamk_f32 v246, v246, 0x3a800000, v197
	v_rsq_f32_e32 v172, v128
	v_rsq_f32_e32 v173, v136
	v_rsq_f32_e32 v174, v164
	v_rsq_f32_e32 v175, v246
	s_nop 0
	v_mul_f32_e32 v172, 0xbfb8aa3b, v172
	v_mul_f32_e32 v173, 0xbfb8aa3b, v173
	v_mul_f32_e32 v174, 0xbfb8aa3b, v174
	v_mul_f32_e32 v175, 0xbfb8aa3b, v175
	s_waitcnt vmcnt(8)
	v_mul_f32_e32 v198, 0xbfb8aa3b, v198
	v_mul_f32_e32 v199, 0xbfb8aa3b, v199
	v_mul_f32_e32 v200, 0xbfb8aa3b, v200
	v_mul_f32_e32 v201, 0xbfb8aa3b, v201
	v_mul_f32_e32 v202, 0xbfb8aa3b, v202
	v_mul_f32_e32 v203, 0xbfb8aa3b, v203
	v_mul_f32_e32 v204, 0xbfb8aa3b, v204
	v_mul_f32_e32 v205, 0xbfb8aa3b, v205
	v_mul_f32_e32 v206, 0xbfb8aa3b, v206
	v_mul_f32_e32 v207, 0xbfb8aa3b, v207
	v_mul_f32_e32 v208, 0xbfb8aa3b, v208
	v_mul_f32_e32 v209, 0xbfb8aa3b, v209
	v_mul_f32_e32 v210, 0xbfb8aa3b, v210
	v_mul_f32_e32 v211, 0xbfb8aa3b, v211
	v_mul_f32_e32 v212, 0xbfb8aa3b, v212
	v_mul_f32_e32 v213, 0xbfb8aa3b, v213
	v_mul_f32_e32 v214, 0xbfb8aa3b, v214
	v_mul_f32_e32 v215, 0xbfb8aa3b, v215
	v_mul_f32_e32 v216, 0xbfb8aa3b, v216
	v_mul_f32_e32 v217, 0xbfb8aa3b, v217
	v_mul_f32_e32 v218, 0xbfb8aa3b, v218
	v_mul_f32_e32 v219, 0xbfb8aa3b, v219
	v_mul_f32_e32 v220, 0xbfb8aa3b, v220
	v_mul_f32_e32 v221, 0xbfb8aa3b, v221
	v_mul_f32_e32 v222, 0xbfb8aa3b, v222
	v_mul_f32_e32 v223, 0xbfb8aa3b, v223
	v_mul_f32_e32 v224, 0xbfb8aa3b, v224
	v_mul_f32_e32 v225, 0xbfb8aa3b, v225
	v_mul_f32_e32 v226, 0xbfb8aa3b, v226
	v_mul_f32_e32 v227, 0xbfb8aa3b, v227
	v_mul_f32_e32 v228, 0xbfb8aa3b, v228
	v_mul_f32_e32 v229, 0xbfb8aa3b, v229
	v_pk_fma_f32 v[0:1], v[0:1], v[172:173], v[198:199] op_sel_hi:[1,0,1]
	v_pk_fma_f32 v[2:3], v[2:3], v[172:173], v[200:201] op_sel_hi:[1,0,1]
	v_pk_fma_f32 v[4:5], v[4:5], v[172:173], v[202:203] op_sel_hi:[1,0,1]
	v_pk_fma_f32 v[6:7], v[6:7], v[172:173], v[204:205] op_sel_hi:[1,0,1]
	v_pk_fma_f32 v[8:9], v[8:9], v[172:173], v[206:207] op_sel_hi:[1,0,1]
	v_pk_fma_f32 v[10:11], v[10:11], v[172:173], v[208:209] op_sel_hi:[1,0,1]
	v_pk_fma_f32 v[12:13], v[12:13], v[172:173], v[210:211] op_sel_hi:[1,0,1]
	v_pk_fma_f32 v[14:15], v[14:15], v[172:173], v[212:213] op_sel_hi:[1,0,1]
	v_pk_fma_f32 v[16:17], v[16:17], v[172:173], v[214:215] op_sel_hi:[1,0,1]
	v_pk_fma_f32 v[18:19], v[18:19], v[172:173], v[216:217] op_sel_hi:[1,0,1]
	v_pk_fma_f32 v[20:21], v[20:21], v[172:173], v[218:219] op_sel_hi:[1,0,1]
	v_pk_fma_f32 v[22:23], v[22:23], v[172:173], v[220:221] op_sel_hi:[1,0,1]
	v_pk_fma_f32 v[24:25], v[24:25], v[172:173], v[222:223] op_sel_hi:[1,0,1]
	v_pk_fma_f32 v[26:27], v[26:27], v[172:173], v[224:225] op_sel_hi:[1,0,1]
	v_pk_fma_f32 v[28:29], v[28:29], v[172:173], v[226:227] op_sel_hi:[1,0,1]
	v_pk_fma_f32 v[30:31], v[30:31], v[172:173], v[228:229] op_sel_hi:[1,0,1]
	v_exp_f32_e32 v0, v0
	v_exp_f32_e32 v1, v1
	v_exp_f32_e32 v2, v2
	v_exp_f32_e32 v3, v3
	v_exp_f32_e32 v4, v4
	v_exp_f32_e32 v5, v5
	v_exp_f32_e32 v6, v6
	v_exp_f32_e32 v7, v7
	v_exp_f32_e32 v8, v8
	v_exp_f32_e32 v9, v9
	v_exp_f32_e32 v10, v10
	v_exp_f32_e32 v11, v11
	v_exp_f32_e32 v12, v12
	v_exp_f32_e32 v13, v13
	v_exp_f32_e32 v14, v14
	v_exp_f32_e32 v15, v15
	v_exp_f32_e32 v16, v16
	v_exp_f32_e32 v17, v17
	v_exp_f32_e32 v18, v18
	v_exp_f32_e32 v19, v19
	v_exp_f32_e32 v20, v20
	v_exp_f32_e32 v21, v21
	v_exp_f32_e32 v22, v22
	v_exp_f32_e32 v23, v23
	v_exp_f32_e32 v24, v24
	v_exp_f32_e32 v25, v25
	v_exp_f32_e32 v26, v26
	v_exp_f32_e32 v27, v27
	v_exp_f32_e32 v28, v28
	v_exp_f32_e32 v29, v29
	v_exp_f32_e32 v30, v30
	v_exp_f32_e32 v31, v31
	v_pk_add_f32 v[0:1], v[0:1], 1.0 op_sel_hi:[1,0]
	v_pk_add_f32 v[2:3], v[2:3], 1.0 op_sel_hi:[1,0]
	v_pk_add_f32 v[4:5], v[4:5], 1.0 op_sel_hi:[1,0]
	v_pk_add_f32 v[6:7], v[6:7], 1.0 op_sel_hi:[1,0]
	v_pk_add_f32 v[8:9], v[8:9], 1.0 op_sel_hi:[1,0]
	v_pk_add_f32 v[10:11], v[10:11], 1.0 op_sel_hi:[1,0]
	v_pk_add_f32 v[12:13], v[12:13], 1.0 op_sel_hi:[1,0]
	v_pk_add_f32 v[14:15], v[14:15], 1.0 op_sel_hi:[1,0]
	v_pk_add_f32 v[16:17], v[16:17], 1.0 op_sel_hi:[1,0]
	v_pk_add_f32 v[18:19], v[18:19], 1.0 op_sel_hi:[1,0]
	v_pk_add_f32 v[20:21], v[20:21], 1.0 op_sel_hi:[1,0]
	v_pk_add_f32 v[22:23], v[22:23], 1.0 op_sel_hi:[1,0]
	v_pk_add_f32 v[24:25], v[24:25], 1.0 op_sel_hi:[1,0]
	v_pk_add_f32 v[26:27], v[26:27], 1.0 op_sel_hi:[1,0]
	v_pk_add_f32 v[28:29], v[28:29], 1.0 op_sel_hi:[1,0]
	v_pk_add_f32 v[30:31], v[30:31], 1.0 op_sel_hi:[1,0]
	v_rcp_f32_e32 v0, v0
	v_rcp_f32_e32 v1, v1
	v_rcp_f32_e32 v2, v2
	v_rcp_f32_e32 v3, v3
	v_rcp_f32_e32 v4, v4
	v_rcp_f32_e32 v5, v5
	v_rcp_f32_e32 v6, v6
	v_rcp_f32_e32 v7, v7
	v_rcp_f32_e32 v8, v8
	v_rcp_f32_e32 v9, v9
	v_rcp_f32_e32 v10, v10
	v_rcp_f32_e32 v11, v11
	v_rcp_f32_e32 v12, v12
	v_rcp_f32_e32 v13, v13
	v_rcp_f32_e32 v14, v14
	v_rcp_f32_e32 v15, v15
	v_rcp_f32_e32 v16, v16
	v_rcp_f32_e32 v17, v17
	v_rcp_f32_e32 v18, v18
	v_rcp_f32_e32 v19, v19
	v_rcp_f32_e32 v20, v20
	v_rcp_f32_e32 v21, v21
	v_rcp_f32_e32 v22, v22
	v_rcp_f32_e32 v23, v23
	v_rcp_f32_e32 v24, v24
	v_rcp_f32_e32 v25, v25
	v_rcp_f32_e32 v26, v26
	v_rcp_f32_e32 v27, v27
	v_rcp_f32_e32 v28, v28
	v_rcp_f32_e32 v29, v29
	v_rcp_f32_e32 v30, v30
	v_rcp_f32_e32 v31, v31
	s_nop 0
	v_cvt_pk_bf16_f32 v0, v0, v1
	v_cvt_pk_bf16_f32 v1, v2, v3
	v_cvt_pk_bf16_f32 v2, v4, v5
	v_cvt_pk_bf16_f32 v3, v6, v7
	v_cvt_pk_bf16_f32 v4, v8, v9
	v_cvt_pk_bf16_f32 v5, v10, v11
	v_cvt_pk_bf16_f32 v6, v12, v13
	v_cvt_pk_bf16_f32 v7, v14, v15
	v_cvt_pk_bf16_f32 v16, v16, v17
	v_cvt_pk_bf16_f32 v17, v18, v19
	v_cvt_pk_bf16_f32 v18, v20, v21
	v_cvt_pk_bf16_f32 v19, v22, v23
	v_cvt_pk_bf16_f32 v20, v24, v25
	v_cvt_pk_bf16_f32 v21, v26, v27
	v_cvt_pk_bf16_f32 v22, v28, v29
	v_cvt_pk_bf16_f32 v23, v30, v31
	v_permlane32_swap_b32_e32 v0, v2
	v_permlane32_swap_b32_e32 v1, v3
	v_permlane32_swap_b32_e32 v4, v6
	v_permlane32_swap_b32_e32 v5, v7
	v_permlane32_swap_b32_e32 v16, v18
	v_permlane32_swap_b32_e32 v17, v19
	v_permlane32_swap_b32_e32 v20, v22
	v_permlane32_swap_b32_e32 v21, v23
	global_store_dwordx4 v181, v[0:3], s[74:75] offset:0
	global_store_dwordx4 v181, v[4:7], s[74:75] offset:32
	global_store_dwordx4 v181, v[16:19], s[74:75] offset:64
	global_store_dwordx4 v181, v[20:23], s[74:75] offset:96
	s_add_u32 s74, s74, 0x44000
	s_addc_u32 s75, s75, 0
	v_pk_fma_f32 v[32:33], v[32:33], v[172:173], v[198:199] op_sel:[0,1,0] op_sel_hi:[1,1,1]
	v_pk_fma_f32 v[34:35], v[34:35], v[172:173], v[200:201] op_sel:[0,1,0] op_sel_hi:[1,1,1]
	v_pk_fma_f32 v[36:37], v[36:37], v[172:173], v[202:203] op_sel:[0,1,0] op_sel_hi:[1,1,1]
	v_pk_fma_f32 v[38:39], v[38:39], v[172:173], v[204:205] op_sel:[0,1,0] op_sel_hi:[1,1,1]
	v_pk_fma_f32 v[40:41], v[40:41], v[172:173], v[206:207] op_sel:[0,1,0] op_sel_hi:[1,1,1]
	v_pk_fma_f32 v[42:43], v[42:43], v[172:173], v[208:209] op_sel:[0,1,0] op_sel_hi:[1,1,1]
	v_pk_fma_f32 v[44:45], v[44:45], v[172:173], v[210:211] op_sel:[0,1,0] op_sel_hi:[1,1,1]
	v_pk_fma_f32 v[46:47], v[46:47], v[172:173], v[212:213] op_sel:[0,1,0] op_sel_hi:[1,1,1]
	v_pk_fma_f32 v[48:49], v[48:49], v[172:173], v[214:215] op_sel:[0,1,0] op_sel_hi:[1,1,1]
	v_pk_fma_f32 v[50:51], v[50:51], v[172:173], v[216:217] op_sel:[0,1,0] op_sel_hi:[1,1,1]
	v_pk_fma_f32 v[52:53], v[52:53], v[172:173], v[218:219] op_sel:[0,1,0] op_sel_hi:[1,1,1]
	v_pk_fma_f32 v[54:55], v[54:55], v[172:173], v[220:221] op_sel:[0,1,0] op_sel_hi:[1,1,1]
	v_pk_fma_f32 v[56:57], v[56:57], v[172:173], v[222:223] op_sel:[0,1,0] op_sel_hi:[1,1,1]
	v_pk_fma_f32 v[58:59], v[58:59], v[172:173], v[224:225] op_sel:[0,1,0] op_sel_hi:[1,1,1]
	v_pk_fma_f32 v[60:61], v[60:61], v[172:173], v[226:227] op_sel:[0,1,0] op_sel_hi:[1,1,1]
	v_pk_fma_f32 v[62:63], v[62:63], v[172:173], v[228:229] op_sel:[0,1,0] op_sel_hi:[1,1,1]
	v_exp_f32_e32 v32, v32
	v_exp_f32_e32 v33, v33
	v_exp_f32_e32 v34, v34
	v_exp_f32_e32 v35, v35
	v_exp_f32_e32 v36, v36
	v_exp_f32_e32 v37, v37
	v_exp_f32_e32 v38, v38
	v_exp_f32_e32 v39, v39
	v_exp_f32_e32 v40, v40
	v_exp_f32_e32 v41, v41
	v_exp_f32_e32 v42, v42
	v_exp_f32_e32 v43, v43
	v_exp_f32_e32 v44, v44
	v_exp_f32_e32 v45, v45
	v_exp_f32_e32 v46, v46
	v_exp_f32_e32 v47, v47
	v_exp_f32_e32 v48, v48
	v_exp_f32_e32 v49, v49
	v_exp_f32_e32 v50, v50
	v_exp_f32_e32 v51, v51
	v_exp_f32_e32 v52, v52
	v_exp_f32_e32 v53, v53
	v_exp_f32_e32 v54, v54
	v_exp_f32_e32 v55, v55
	v_exp_f32_e32 v56, v56
	v_exp_f32_e32 v57, v57
	v_exp_f32_e32 v58, v58
	v_exp_f32_e32 v59, v59
	v_exp_f32_e32 v60, v60
	v_exp_f32_e32 v61, v61
	v_exp_f32_e32 v62, v62
	v_exp_f32_e32 v63, v63
	v_pk_add_f32 v[32:33], v[32:33], 1.0 op_sel_hi:[1,0]
	v_pk_add_f32 v[34:35], v[34:35], 1.0 op_sel_hi:[1,0]
	v_pk_add_f32 v[36:37], v[36:37], 1.0 op_sel_hi:[1,0]
	v_pk_add_f32 v[38:39], v[38:39], 1.0 op_sel_hi:[1,0]
	v_pk_add_f32 v[40:41], v[40:41], 1.0 op_sel_hi:[1,0]
	v_pk_add_f32 v[42:43], v[42:43], 1.0 op_sel_hi:[1,0]
	v_pk_add_f32 v[44:45], v[44:45], 1.0 op_sel_hi:[1,0]
	v_pk_add_f32 v[46:47], v[46:47], 1.0 op_sel_hi:[1,0]
	v_pk_add_f32 v[48:49], v[48:49], 1.0 op_sel_hi:[1,0]
	v_pk_add_f32 v[50:51], v[50:51], 1.0 op_sel_hi:[1,0]
	v_pk_add_f32 v[52:53], v[52:53], 1.0 op_sel_hi:[1,0]
	v_pk_add_f32 v[54:55], v[54:55], 1.0 op_sel_hi:[1,0]
	v_pk_add_f32 v[56:57], v[56:57], 1.0 op_sel_hi:[1,0]
	v_pk_add_f32 v[58:59], v[58:59], 1.0 op_sel_hi:[1,0]
	v_pk_add_f32 v[60:61], v[60:61], 1.0 op_sel_hi:[1,0]
	v_pk_add_f32 v[62:63], v[62:63], 1.0 op_sel_hi:[1,0]
	v_rcp_f32_e32 v32, v32
	v_rcp_f32_e32 v33, v33
	v_rcp_f32_e32 v34, v34
	v_rcp_f32_e32 v35, v35
	v_rcp_f32_e32 v36, v36
	v_rcp_f32_e32 v37, v37
	v_rcp_f32_e32 v38, v38
	v_rcp_f32_e32 v39, v39
	v_rcp_f32_e32 v40, v40
	v_rcp_f32_e32 v41, v41
	v_rcp_f32_e32 v42, v42
	v_rcp_f32_e32 v43, v43
	v_rcp_f32_e32 v44, v44
	v_rcp_f32_e32 v45, v45
	v_rcp_f32_e32 v46, v46
	v_rcp_f32_e32 v47, v47
	v_rcp_f32_e32 v48, v48
	v_rcp_f32_e32 v49, v49
	v_rcp_f32_e32 v50, v50
	v_rcp_f32_e32 v51, v51
	v_rcp_f32_e32 v52, v52
	v_rcp_f32_e32 v53, v53
	v_rcp_f32_e32 v54, v54
	v_rcp_f32_e32 v55, v55
	v_rcp_f32_e32 v56, v56
	v_rcp_f32_e32 v57, v57
	v_rcp_f32_e32 v58, v58
	v_rcp_f32_e32 v59, v59
	v_rcp_f32_e32 v60, v60
	v_rcp_f32_e32 v61, v61
	v_rcp_f32_e32 v62, v62
	v_rcp_f32_e32 v63, v63
	s_nop 0
	v_cvt_pk_bf16_f32 v32, v32, v33
	v_cvt_pk_bf16_f32 v33, v34, v35
	v_cvt_pk_bf16_f32 v34, v36, v37
	v_cvt_pk_bf16_f32 v35, v38, v39
	v_cvt_pk_bf16_f32 v36, v40, v41
	v_cvt_pk_bf16_f32 v37, v42, v43
	v_cvt_pk_bf16_f32 v38, v44, v45
	v_cvt_pk_bf16_f32 v39, v46, v47
	v_cvt_pk_bf16_f32 v48, v48, v49
	v_cvt_pk_bf16_f32 v49, v50, v51
	v_cvt_pk_bf16_f32 v50, v52, v53
	v_cvt_pk_bf16_f32 v51, v54, v55
	v_cvt_pk_bf16_f32 v52, v56, v57
	v_cvt_pk_bf16_f32 v53, v58, v59
	v_cvt_pk_bf16_f32 v54, v60, v61
	v_cvt_pk_bf16_f32 v55, v62, v63
	v_permlane32_swap_b32_e32 v32, v34
	v_permlane32_swap_b32_e32 v33, v35
	v_permlane32_swap_b32_e32 v36, v38
	v_permlane32_swap_b32_e32 v37, v39
	v_permlane32_swap_b32_e32 v48, v50
	v_permlane32_swap_b32_e32 v49, v51
	v_permlane32_swap_b32_e32 v52, v54
	v_permlane32_swap_b32_e32 v53, v55
	global_store_dwordx4 v181, v[32:35], s[74:75] offset:0
	global_store_dwordx4 v181, v[36:39], s[74:75] offset:32
	global_store_dwordx4 v181, v[48:51], s[74:75] offset:64
	global_store_dwordx4 v181, v[52:55], s[74:75] offset:96
	s_add_u32 s74, s74, 0x44000
	s_addc_u32 s75, s75, 0
	v_pk_fma_f32 v[64:65], v[64:65], v[174:175], v[198:199] op_sel_hi:[1,0,1]
	v_pk_fma_f32 v[66:67], v[66:67], v[174:175], v[200:201] op_sel_hi:[1,0,1]
	v_pk_fma_f32 v[68:69], v[68:69], v[174:175], v[202:203] op_sel_hi:[1,0,1]
	v_pk_fma_f32 v[70:71], v[70:71], v[174:175], v[204:205] op_sel_hi:[1,0,1]
	v_pk_fma_f32 v[72:73], v[72:73], v[174:175], v[206:207] op_sel_hi:[1,0,1]
	v_pk_fma_f32 v[74:75], v[74:75], v[174:175], v[208:209] op_sel_hi:[1,0,1]
	v_pk_fma_f32 v[76:77], v[76:77], v[174:175], v[210:211] op_sel_hi:[1,0,1]
	v_pk_fma_f32 v[78:79], v[78:79], v[174:175], v[212:213] op_sel_hi:[1,0,1]
	v_pk_fma_f32 v[80:81], v[80:81], v[174:175], v[214:215] op_sel_hi:[1,0,1]
	v_pk_fma_f32 v[82:83], v[82:83], v[174:175], v[216:217] op_sel_hi:[1,0,1]
	v_pk_fma_f32 v[84:85], v[84:85], v[174:175], v[218:219] op_sel_hi:[1,0,1]
	v_pk_fma_f32 v[86:87], v[86:87], v[174:175], v[220:221] op_sel_hi:[1,0,1]
	v_pk_fma_f32 v[88:89], v[88:89], v[174:175], v[222:223] op_sel_hi:[1,0,1]
	v_pk_fma_f32 v[90:91], v[90:91], v[174:175], v[224:225] op_sel_hi:[1,0,1]
	v_pk_fma_f32 v[92:93], v[92:93], v[174:175], v[226:227] op_sel_hi:[1,0,1]
	v_pk_fma_f32 v[94:95], v[94:95], v[174:175], v[228:229] op_sel_hi:[1,0,1]
	v_exp_f32_e32 v64, v64
	v_exp_f32_e32 v65, v65
	v_exp_f32_e32 v66, v66
	v_exp_f32_e32 v67, v67
	v_exp_f32_e32 v68, v68
	v_exp_f32_e32 v69, v69
	v_exp_f32_e32 v70, v70
	v_exp_f32_e32 v71, v71
	v_exp_f32_e32 v72, v72
	v_exp_f32_e32 v73, v73
	v_exp_f32_e32 v74, v74
	v_exp_f32_e32 v75, v75
	v_exp_f32_e32 v76, v76
	v_exp_f32_e32 v77, v77
	v_exp_f32_e32 v78, v78
	v_exp_f32_e32 v79, v79
	v_exp_f32_e32 v80, v80
	v_exp_f32_e32 v81, v81
	v_exp_f32_e32 v82, v82
	v_exp_f32_e32 v83, v83
	v_exp_f32_e32 v84, v84
	v_exp_f32_e32 v85, v85
	v_exp_f32_e32 v86, v86
	v_exp_f32_e32 v87, v87
	v_exp_f32_e32 v88, v88
	v_exp_f32_e32 v89, v89
	v_exp_f32_e32 v90, v90
	v_exp_f32_e32 v91, v91
	v_exp_f32_e32 v92, v92
	v_exp_f32_e32 v93, v93
	v_exp_f32_e32 v94, v94
	v_exp_f32_e32 v95, v95
	v_pk_add_f32 v[64:65], v[64:65], 1.0 op_sel_hi:[1,0]
	v_pk_add_f32 v[66:67], v[66:67], 1.0 op_sel_hi:[1,0]
	v_pk_add_f32 v[68:69], v[68:69], 1.0 op_sel_hi:[1,0]
	v_pk_add_f32 v[70:71], v[70:71], 1.0 op_sel_hi:[1,0]
	v_pk_add_f32 v[72:73], v[72:73], 1.0 op_sel_hi:[1,0]
	v_pk_add_f32 v[74:75], v[74:75], 1.0 op_sel_hi:[1,0]
	v_pk_add_f32 v[76:77], v[76:77], 1.0 op_sel_hi:[1,0]
	v_pk_add_f32 v[78:79], v[78:79], 1.0 op_sel_hi:[1,0]
	v_pk_add_f32 v[80:81], v[80:81], 1.0 op_sel_hi:[1,0]
	v_pk_add_f32 v[82:83], v[82:83], 1.0 op_sel_hi:[1,0]
	v_pk_add_f32 v[84:85], v[84:85], 1.0 op_sel_hi:[1,0]
	v_pk_add_f32 v[86:87], v[86:87], 1.0 op_sel_hi:[1,0]
	v_pk_add_f32 v[88:89], v[88:89], 1.0 op_sel_hi:[1,0]
	v_pk_add_f32 v[90:91], v[90:91], 1.0 op_sel_hi:[1,0]
	v_pk_add_f32 v[92:93], v[92:93], 1.0 op_sel_hi:[1,0]
	v_pk_add_f32 v[94:95], v[94:95], 1.0 op_sel_hi:[1,0]
	v_rcp_f32_e32 v64, v64
	v_rcp_f32_e32 v65, v65
	v_rcp_f32_e32 v66, v66
	v_rcp_f32_e32 v67, v67
	v_rcp_f32_e32 v68, v68
	v_rcp_f32_e32 v69, v69
	v_rcp_f32_e32 v70, v70
	v_rcp_f32_e32 v71, v71
	v_rcp_f32_e32 v72, v72
	v_rcp_f32_e32 v73, v73
	v_rcp_f32_e32 v74, v74
	v_rcp_f32_e32 v75, v75
	v_rcp_f32_e32 v76, v76
	v_rcp_f32_e32 v77, v77
	v_rcp_f32_e32 v78, v78
	v_rcp_f32_e32 v79, v79
	v_rcp_f32_e32 v80, v80
	v_rcp_f32_e32 v81, v81
	v_rcp_f32_e32 v82, v82
	v_rcp_f32_e32 v83, v83
	v_rcp_f32_e32 v84, v84
	v_rcp_f32_e32 v85, v85
	v_rcp_f32_e32 v86, v86
	v_rcp_f32_e32 v87, v87
	v_rcp_f32_e32 v88, v88
	v_rcp_f32_e32 v89, v89
	v_rcp_f32_e32 v90, v90
	v_rcp_f32_e32 v91, v91
	v_rcp_f32_e32 v92, v92
	v_rcp_f32_e32 v93, v93
	v_rcp_f32_e32 v94, v94
	v_rcp_f32_e32 v95, v95
	s_nop 0
	v_cvt_pk_bf16_f32 v64, v64, v65
	v_cvt_pk_bf16_f32 v65, v66, v67
	v_cvt_pk_bf16_f32 v66, v68, v69
	v_cvt_pk_bf16_f32 v67, v70, v71
	v_cvt_pk_bf16_f32 v68, v72, v73
	v_cvt_pk_bf16_f32 v69, v74, v75
	v_cvt_pk_bf16_f32 v70, v76, v77
	v_cvt_pk_bf16_f32 v71, v78, v79
	v_cvt_pk_bf16_f32 v80, v80, v81
	v_cvt_pk_bf16_f32 v81, v82, v83
	v_cvt_pk_bf16_f32 v82, v84, v85
	v_cvt_pk_bf16_f32 v83, v86, v87
	v_cvt_pk_bf16_f32 v84, v88, v89
	v_cvt_pk_bf16_f32 v85, v90, v91
	v_cvt_pk_bf16_f32 v86, v92, v93
	v_cvt_pk_bf16_f32 v87, v94, v95
	v_permlane32_swap_b32_e32 v64, v66
	v_permlane32_swap_b32_e32 v65, v67
	v_permlane32_swap_b32_e32 v68, v70
	v_permlane32_swap_b32_e32 v69, v71
	v_permlane32_swap_b32_e32 v80, v82
	v_permlane32_swap_b32_e32 v81, v83
	v_permlane32_swap_b32_e32 v84, v86
	v_permlane32_swap_b32_e32 v85, v87
	global_store_dwordx4 v181, v[64:67], s[74:75] offset:0
	global_store_dwordx4 v181, v[68:71], s[74:75] offset:32
	global_store_dwordx4 v181, v[80:83], s[74:75] offset:64
	global_store_dwordx4 v181, v[84:87], s[74:75] offset:96
	s_add_u32 s74, s74, 0x44000
	s_addc_u32 s75, s75, 0
	v_pk_fma_f32 v[96:97], v[96:97], v[174:175], v[198:199] op_sel:[0,1,0] op_sel_hi:[1,1,1]
	v_pk_fma_f32 v[98:99], v[98:99], v[174:175], v[200:201] op_sel:[0,1,0] op_sel_hi:[1,1,1]
	v_pk_fma_f32 v[100:101], v[100:101], v[174:175], v[202:203] op_sel:[0,1,0] op_sel_hi:[1,1,1]
	v_pk_fma_f32 v[102:103], v[102:103], v[174:175], v[204:205] op_sel:[0,1,0] op_sel_hi:[1,1,1]
	v_pk_fma_f32 v[104:105], v[104:105], v[174:175], v[206:207] op_sel:[0,1,0] op_sel_hi:[1,1,1]
	v_pk_fma_f32 v[106:107], v[106:107], v[174:175], v[208:209] op_sel:[0,1,0] op_sel_hi:[1,1,1]
	v_pk_fma_f32 v[108:109], v[108:109], v[174:175], v[210:211] op_sel:[0,1,0] op_sel_hi:[1,1,1]
	v_pk_fma_f32 v[110:111], v[110:111], v[174:175], v[212:213] op_sel:[0,1,0] op_sel_hi:[1,1,1]
	v_pk_fma_f32 v[112:113], v[112:113], v[174:175], v[214:215] op_sel:[0,1,0] op_sel_hi:[1,1,1]
	v_pk_fma_f32 v[114:115], v[114:115], v[174:175], v[216:217] op_sel:[0,1,0] op_sel_hi:[1,1,1]
	v_pk_fma_f32 v[116:117], v[116:117], v[174:175], v[218:219] op_sel:[0,1,0] op_sel_hi:[1,1,1]
	v_pk_fma_f32 v[118:119], v[118:119], v[174:175], v[220:221] op_sel:[0,1,0] op_sel_hi:[1,1,1]
	v_pk_fma_f32 v[120:121], v[120:121], v[174:175], v[222:223] op_sel:[0,1,0] op_sel_hi:[1,1,1]
	v_pk_fma_f32 v[122:123], v[122:123], v[174:175], v[224:225] op_sel:[0,1,0] op_sel_hi:[1,1,1]
	v_pk_fma_f32 v[124:125], v[124:125], v[174:175], v[226:227] op_sel:[0,1,0] op_sel_hi:[1,1,1]
	v_pk_fma_f32 v[126:127], v[126:127], v[174:175], v[228:229] op_sel:[0,1,0] op_sel_hi:[1,1,1]
	v_exp_f32_e32 v96, v96
	v_exp_f32_e32 v97, v97
	v_exp_f32_e32 v98, v98
	v_exp_f32_e32 v99, v99
	v_exp_f32_e32 v100, v100
	v_exp_f32_e32 v101, v101
	v_exp_f32_e32 v102, v102
	v_exp_f32_e32 v103, v103
	v_exp_f32_e32 v104, v104
	v_exp_f32_e32 v105, v105
	v_exp_f32_e32 v106, v106
	v_exp_f32_e32 v107, v107
	v_exp_f32_e32 v108, v108
	v_exp_f32_e32 v109, v109
	v_exp_f32_e32 v110, v110
	v_exp_f32_e32 v111, v111
	v_exp_f32_e32 v112, v112
	v_exp_f32_e32 v113, v113
	v_exp_f32_e32 v114, v114
	v_exp_f32_e32 v115, v115
	v_exp_f32_e32 v116, v116
	v_exp_f32_e32 v117, v117
	v_exp_f32_e32 v118, v118
	v_exp_f32_e32 v119, v119
	v_exp_f32_e32 v120, v120
	v_exp_f32_e32 v121, v121
	v_exp_f32_e32 v122, v122
	v_exp_f32_e32 v123, v123
	v_exp_f32_e32 v124, v124
	v_exp_f32_e32 v125, v125
	v_exp_f32_e32 v126, v126
	v_exp_f32_e32 v127, v127
	v_pk_add_f32 v[96:97], v[96:97], 1.0 op_sel_hi:[1,0]
	v_pk_add_f32 v[98:99], v[98:99], 1.0 op_sel_hi:[1,0]
	v_pk_add_f32 v[100:101], v[100:101], 1.0 op_sel_hi:[1,0]
	v_pk_add_f32 v[102:103], v[102:103], 1.0 op_sel_hi:[1,0]
	v_pk_add_f32 v[104:105], v[104:105], 1.0 op_sel_hi:[1,0]
	v_pk_add_f32 v[106:107], v[106:107], 1.0 op_sel_hi:[1,0]
	v_pk_add_f32 v[108:109], v[108:109], 1.0 op_sel_hi:[1,0]
	v_pk_add_f32 v[110:111], v[110:111], 1.0 op_sel_hi:[1,0]
	v_pk_add_f32 v[112:113], v[112:113], 1.0 op_sel_hi:[1,0]
	v_pk_add_f32 v[114:115], v[114:115], 1.0 op_sel_hi:[1,0]
	v_pk_add_f32 v[116:117], v[116:117], 1.0 op_sel_hi:[1,0]
	v_pk_add_f32 v[118:119], v[118:119], 1.0 op_sel_hi:[1,0]
	v_pk_add_f32 v[120:121], v[120:121], 1.0 op_sel_hi:[1,0]
	v_pk_add_f32 v[122:123], v[122:123], 1.0 op_sel_hi:[1,0]
	v_pk_add_f32 v[124:125], v[124:125], 1.0 op_sel_hi:[1,0]
	v_pk_add_f32 v[126:127], v[126:127], 1.0 op_sel_hi:[1,0]
	v_rcp_f32_e32 v96, v96
	v_rcp_f32_e32 v97, v97
	v_rcp_f32_e32 v98, v98
	v_rcp_f32_e32 v99, v99
	v_rcp_f32_e32 v100, v100
	v_rcp_f32_e32 v101, v101
	v_rcp_f32_e32 v102, v102
	v_rcp_f32_e32 v103, v103
	v_rcp_f32_e32 v104, v104
	v_rcp_f32_e32 v105, v105
	v_rcp_f32_e32 v106, v106
	v_rcp_f32_e32 v107, v107
	v_rcp_f32_e32 v108, v108
	v_rcp_f32_e32 v109, v109
	v_rcp_f32_e32 v110, v110
	v_rcp_f32_e32 v111, v111
	v_rcp_f32_e32 v112, v112
	v_rcp_f32_e32 v113, v113
	v_rcp_f32_e32 v114, v114
	v_rcp_f32_e32 v115, v115
	v_rcp_f32_e32 v116, v116
	v_rcp_f32_e32 v117, v117
	v_rcp_f32_e32 v118, v118
	v_rcp_f32_e32 v119, v119
	v_rcp_f32_e32 v120, v120
	v_rcp_f32_e32 v121, v121
	v_rcp_f32_e32 v122, v122
	v_rcp_f32_e32 v123, v123
	v_rcp_f32_e32 v124, v124
	v_rcp_f32_e32 v125, v125
	v_rcp_f32_e32 v126, v126
	v_rcp_f32_e32 v127, v127
	s_nop 0
	v_cvt_pk_bf16_f32 v96, v96, v97
	v_cvt_pk_bf16_f32 v97, v98, v99
	v_cvt_pk_bf16_f32 v98, v100, v101
	v_cvt_pk_bf16_f32 v99, v102, v103
	v_cvt_pk_bf16_f32 v100, v104, v105
	v_cvt_pk_bf16_f32 v101, v106, v107
	v_cvt_pk_bf16_f32 v102, v108, v109
	v_cvt_pk_bf16_f32 v103, v110, v111
	v_cvt_pk_bf16_f32 v112, v112, v113
	v_cvt_pk_bf16_f32 v113, v114, v115
	v_cvt_pk_bf16_f32 v114, v116, v117
	v_cvt_pk_bf16_f32 v115, v118, v119
	v_cvt_pk_bf16_f32 v116, v120, v121
	v_cvt_pk_bf16_f32 v117, v122, v123
	v_cvt_pk_bf16_f32 v118, v124, v125
	v_cvt_pk_bf16_f32 v119, v126, v127
	v_permlane32_swap_b32_e32 v96, v98
	v_permlane32_swap_b32_e32 v97, v99
	v_permlane32_swap_b32_e32 v100, v102
	v_permlane32_swap_b32_e32 v101, v103
	v_permlane32_swap_b32_e32 v112, v114
	v_permlane32_swap_b32_e32 v113, v115
	v_permlane32_swap_b32_e32 v116, v118
	v_permlane32_swap_b32_e32 v117, v119
	global_store_dwordx4 v181, v[96:99], s[74:75] offset:0
	global_store_dwordx4 v181, v[100:103], s[74:75] offset:32
	global_store_dwordx4 v181, v[112:115], s[74:75] offset:64
	global_store_dwordx4 v181, v[116:119], s[74:75] offset:96
	s_branch .Lpe_ret_L1
.Lpe_vt_L1:
	s_lshl_b32 s35, s34, 2
	s_add_u32 s35, s35, s28
	s_add_u32 s36, s28, 6
	s_cmp_eq_u32 s25, 8
	s_cselect_b32 s35, s36, s35
	s_lshr_b32 s36, s29, 11
	s_mul_i32 s36, s36, 10
	s_add_u32 s36, s36, s35
	s_lshl_b32 s36, s36, 18
	s_and_b32 s37, s29, 0x7ff
	s_lshl_b32 s37, s37, 1
	s_add_u32 s36, s36, s37
	s_add_u32 s38, s72, 0x14920000
	s_addc_u32 s39, s73, 0
	s_add_u32 s38, s38, s36
	s_addc_u32 s39, s39, 0
	s_mul_i32 s36, s26, 10240
	s_add_u32 s36, s36, 0x10000
	v_lshlrev_b32_e32 v180, 1, v197
	v_mul_u32_u24_e32 v181, 36, v146
	v_add3_u32 v180, v180, v181, s36
	v_lshrrev_b32_e32 v181, 3, v179
	v_and_b32_e32 v146, 7, v179
	v_lshlrev_b32_e32 v146, 4, v146
	v_mul_u32_u24_e32 v198, 144, v181
	v_add3_u32 v198, v198, v146, s36
	v_lshl_add_u32 v199, v181, 12, v146
	s_add_u32 s76, s99, s90
	s_cmp_lt_u32 s76, 0x440
	s_cselect_b32 s80, 1, 0
	s_cselect_b32 s83, 0x200000, 0
	s_lshl_b32 s76, s24, 19
	s_lshl_b32 s77, s26, 16
	s_add_u32 s76, s76, s77
	s_and_b32 s77, s24, 7
	s_lshl_b32 s77, s77, 8
	s_add_u32 s76, s76, s77
	s_add_u32 s78, s72, 0xa120000
	s_addc_u32 s79, s73, 0
	s_add_u32 s78, s78, s76
	s_addc_u32 s79, s79, 0
	s_lshl_b32 s76, s25, 19
	s_add_u32 s76, s76, s83
	s_add_u32 s76, s76, s77
	s_lshl_b32 s77, s26, 16
	s_add_u32 s76, s76, s77
	s_add_u32 s82, s72, 0x880000
	s_addc_u32 s83, s73, 0
	s_add_u32 s82, s82, s76
	s_addc_u32 s83, s83, 0
	s_lshl_b32 s76, s26, 12
	s_mov_b32 m0, s76
	s_nop 0
	global_load_lds_dwordx4 v177, s[78:79]
	s_add_u32 s78, s78, 0x4000
	s_addc_u32 s79, s79, 0
	s_add_u32 s76, s76, 0x400
	s_mov_b32 m0, s76
	s_nop 0
	global_load_lds_dwordx4 v185, s[78:79]
	s_add_u32 s78, s78, 0x4000
	s_addc_u32 s79, s79, 0
	s_add_u32 s76, s76, 0x400
	s_mov_b32 m0, s76
	s_nop 0
	global_load_lds_dwordx4 v177, s[78:79]
	s_add_u32 s78, s78, 0x4000
	s_addc_u32 s79, s79, 0
	s_add_u32 s76, s76, 0x400
	s_mov_b32 m0, s76
	s_nop 0
	global_load_lds_dwordx4 v185, s[78:79]
	s_add_u32 s78, s78, 0x4000
	s_addc_u32 s79, s79, 0
	s_add_u32 s76, s76, 0x400
	s_add_u32 s76, s76, 0x7000
	s_mov_b32 m0, s76
	s_nop 0
	global_load_lds_dwordx4 v177, s[82:83]
	s_add_u32 s82, s82, 0x4000
	s_addc_u32 s83, s83, 0
	s_add_u32 s76, s76, 0x400
	s_mov_b32 m0, s76
	s_nop 0
	global_load_lds_dwordx4 v185, s[82:83]
	s_add_u32 s82, s82, 0x4000
	s_addc_u32 s83, s83, 0
	s_add_u32 s76, s76, 0x400
	s_mov_b32 m0, s76
	s_nop 0
	global_load_lds_dwordx4 v177, s[82:83]
	s_add_u32 s82, s82, 0x4000
	s_addc_u32 s83, s83, 0
	s_add_u32 s76, s76, 0x400
	s_mov_b32 m0, s76
	s_nop 0
	global_load_lds_dwordx4 v185, s[82:83]
	s_add_u32 s82, s82, 0x4000
	s_addc_u32 s83, s83, 0
	s_add_u32 s76, s76, 0x400
	s_waitcnt vmcnt(8)
	v_mov_b32_e32 v197, 0x358637bd
	v_pk_add_f32 v[128:129], v[128:129], v[130:131]
	v_pk_add_f32 v[132:133], v[132:133], v[134:135]
	v_pk_add_f32 v[136:137], v[136:137], v[138:139]
	v_pk_add_f32 v[140:141], v[140:141], v[142:143]
	v_pk_add_f32 v[164:165], v[164:165], v[166:167]
	v_pk_add_f32 v[168:169], v[168:169], v[170:171]
	v_pk_add_f32 v[246:247], v[246:247], v[248:249]
	v_pk_add_f32 v[250:251], v[250:251], v[252:253]
	v_pk_add_f32 v[128:129], v[128:129], v[132:133]
	v_pk_add_f32 v[136:137], v[136:137], v[140:141]
	v_pk_add_f32 v[164:165], v[164:165], v[168:169]
	v_pk_add_f32 v[246:247], v[246:247], v[250:251]
	v_add_f32_e32 v128, v128, v129
	v_add_f32_e32 v136, v136, v137
	v_add_f32_e32 v164, v164, v165
	v_add_f32_e32 v246, v246, v247
	v_fmamk_f32 v128, v128, 0x3a800000, v197
	v_fmamk_f32 v136, v136, 0x3a800000, v197
	v_fmamk_f32 v164, v164, 0x3a800000, v197
	v_fmamk_f32 v246, v246, 0x3a800000, v197
	v_rsq_f32_e32 v172, v128
	v_rsq_f32_e32 v173, v136
	v_rsq_f32_e32 v174, v164
	v_rsq_f32_e32 v175, v246
	s_nop 0
	v_pk_mul_f32 v[0:1], v[0:1], v[172:173] op_sel_hi:[1,0]
	v_pk_mul_f32 v[2:3], v[2:3], v[172:173] op_sel_hi:[1,0]
	v_pk_mul_f32 v[4:5], v[4:5], v[172:173] op_sel_hi:[1,0]
	v_pk_mul_f32 v[6:7], v[6:7], v[172:173] op_sel_hi:[1,0]
	v_pk_mul_f32 v[8:9], v[8:9], v[172:173] op_sel_hi:[1,0]
	v_pk_mul_f32 v[10:11], v[10:11], v[172:173] op_sel_hi:[1,0]
	v_pk_mul_f32 v[12:13], v[12:13], v[172:173] op_sel_hi:[1,0]
	v_pk_mul_f32 v[14:15], v[14:15], v[172:173] op_sel_hi:[1,0]
	v_pk_mul_f32 v[16:17], v[16:17], v[172:173] op_sel_hi:[1,0]
	v_pk_mul_f32 v[18:19], v[18:19], v[172:173] op_sel_hi:[1,0]
	v_pk_mul_f32 v[20:21], v[20:21], v[172:173] op_sel_hi:[1,0]
	v_pk_mul_f32 v[22:23], v[22:23], v[172:173] op_sel_hi:[1,0]
	v_pk_mul_f32 v[24:25], v[24:25], v[172:173] op_sel_hi:[1,0]
	v_pk_mul_f32 v[26:27], v[26:27], v[172:173] op_sel_hi:[1,0]
	v_pk_mul_f32 v[28:29], v[28:29], v[172:173] op_sel_hi:[1,0]
	v_pk_mul_f32 v[30:31], v[30:31], v[172:173] op_sel_hi:[1,0]
	v_pk_mul_f32 v[32:33], v[32:33], v[172:173] op_sel:[0,1] op_sel_hi:[1,1]
	v_pk_mul_f32 v[34:35], v[34:35], v[172:173] op_sel:[0,1] op_sel_hi:[1,1]
	v_pk_mul_f32 v[36:37], v[36:37], v[172:173] op_sel:[0,1] op_sel_hi:[1,1]
	v_pk_mul_f32 v[38:39], v[38:39], v[172:173] op_sel:[0,1] op_sel_hi:[1,1]
	v_pk_mul_f32 v[40:41], v[40:41], v[172:173] op_sel:[0,1] op_sel_hi:[1,1]
	v_pk_mul_f32 v[42:43], v[42:43], v[172:173] op_sel:[0,1] op_sel_hi:[1,1]
	v_pk_mul_f32 v[44:45], v[44:45], v[172:173] op_sel:[0,1] op_sel_hi:[1,1]
	v_pk_mul_f32 v[46:47], v[46:47], v[172:173] op_sel:[0,1] op_sel_hi:[1,1]
	v_pk_mul_f32 v[48:49], v[48:49], v[172:173] op_sel:[0,1] op_sel_hi:[1,1]
	v_pk_mul_f32 v[50:51], v[50:51], v[172:173] op_sel:[0,1] op_sel_hi:[1,1]
	v_pk_mul_f32 v[52:53], v[52:53], v[172:173] op_sel:[0,1] op_sel_hi:[1,1]
	v_pk_mul_f32 v[54:55], v[54:55], v[172:173] op_sel:[0,1] op_sel_hi:[1,1]
	v_pk_mul_f32 v[56:57], v[56:57], v[172:173] op_sel:[0,1] op_sel_hi:[1,1]
	v_pk_mul_f32 v[58:59], v[58:59], v[172:173] op_sel:[0,1] op_sel_hi:[1,1]
	v_pk_mul_f32 v[60:61], v[60:61], v[172:173] op_sel:[0,1] op_sel_hi:[1,1]
	v_pk_mul_f32 v[62:63], v[62:63], v[172:173] op_sel:[0,1] op_sel_hi:[1,1]
	v_pk_mul_f32 v[64:65], v[64:65], v[174:175] op_sel_hi:[1,0]
	v_pk_mul_f32 v[66:67], v[66:67], v[174:175] op_sel_hi:[1,0]
	v_pk_mul_f32 v[68:69], v[68:69], v[174:175] op_sel_hi:[1,0]
	v_pk_mul_f32 v[70:71], v[70:71], v[174:175] op_sel_hi:[1,0]
	v_pk_mul_f32 v[72:73], v[72:73], v[174:175] op_sel_hi:[1,0]
	v_pk_mul_f32 v[74:75], v[74:75], v[174:175] op_sel_hi:[1,0]
	v_pk_mul_f32 v[76:77], v[76:77], v[174:175] op_sel_hi:[1,0]
	v_pk_mul_f32 v[78:79], v[78:79], v[174:175] op_sel_hi:[1,0]
	v_pk_mul_f32 v[80:81], v[80:81], v[174:175] op_sel_hi:[1,0]
	v_pk_mul_f32 v[82:83], v[82:83], v[174:175] op_sel_hi:[1,0]
	v_pk_mul_f32 v[84:85], v[84:85], v[174:175] op_sel_hi:[1,0]
	v_pk_mul_f32 v[86:87], v[86:87], v[174:175] op_sel_hi:[1,0]
	v_pk_mul_f32 v[88:89], v[88:89], v[174:175] op_sel_hi:[1,0]
	v_pk_mul_f32 v[90:91], v[90:91], v[174:175] op_sel_hi:[1,0]
	v_pk_mul_f32 v[92:93], v[92:93], v[174:175] op_sel_hi:[1,0]
	v_pk_mul_f32 v[94:95], v[94:95], v[174:175] op_sel_hi:[1,0]
	v_pk_mul_f32 v[96:97], v[96:97], v[174:175] op_sel:[0,1] op_sel_hi:[1,1]
	v_pk_mul_f32 v[98:99], v[98:99], v[174:175] op_sel:[0,1] op_sel_hi:[1,1]
	v_pk_mul_f32 v[100:101], v[100:101], v[174:175] op_sel:[0,1] op_sel_hi:[1,1]
	v_pk_mul_f32 v[102:103], v[102:103], v[174:175] op_sel:[0,1] op_sel_hi:[1,1]
	v_pk_mul_f32 v[104:105], v[104:105], v[174:175] op_sel:[0,1] op_sel_hi:[1,1]
	v_pk_mul_f32 v[106:107], v[106:107], v[174:175] op_sel:[0,1] op_sel_hi:[1,1]
	v_pk_mul_f32 v[108:109], v[108:109], v[174:175] op_sel:[0,1] op_sel_hi:[1,1]
	v_pk_mul_f32 v[110:111], v[110:111], v[174:175] op_sel:[0,1] op_sel_hi:[1,1]
	v_pk_mul_f32 v[112:113], v[112:113], v[174:175] op_sel:[0,1] op_sel_hi:[1,1]
	v_pk_mul_f32 v[114:115], v[114:115], v[174:175] op_sel:[0,1] op_sel_hi:[1,1]
	v_pk_mul_f32 v[116:117], v[116:117], v[174:175] op_sel:[0,1] op_sel_hi:[1,1]
	v_pk_mul_f32 v[118:119], v[118:119], v[174:175] op_sel:[0,1] op_sel_hi:[1,1]
	v_pk_mul_f32 v[120:121], v[120:121], v[174:175] op_sel:[0,1] op_sel_hi:[1,1]
	v_pk_mul_f32 v[122:123], v[122:123], v[174:175] op_sel:[0,1] op_sel_hi:[1,1]
	v_pk_mul_f32 v[124:125], v[124:125], v[174:175] op_sel:[0,1] op_sel_hi:[1,1]
	v_pk_mul_f32 v[126:127], v[126:127], v[174:175] op_sel:[0,1] op_sel_hi:[1,1]
	v_cvt_pk_bf16_f32 v0, v0, v1
	v_cvt_pk_bf16_f32 v1, v2, v3
	v_cvt_pk_bf16_f32 v2, v4, v5
	v_cvt_pk_bf16_f32 v3, v6, v7
	v_cvt_pk_bf16_f32 v4, v8, v9
	v_cvt_pk_bf16_f32 v5, v10, v11
	v_cvt_pk_bf16_f32 v6, v12, v13
	v_cvt_pk_bf16_f32 v7, v14, v15
	ds_write_b16 v180, v0 offset:0
	ds_write_b16_d16_hi v180, v0 offset:144
	ds_write_b16 v180, v1 offset:288
	ds_write_b16_d16_hi v180, v1 offset:432
	ds_write_b16 v180, v2 offset:1152
	ds_write_b16_d16_hi v180, v2 offset:1296
	ds_write_b16 v180, v3 offset:1440
	ds_write_b16_d16_hi v180, v3 offset:1584
	ds_write_b16 v180, v4 offset:2304
	ds_write_b16_d16_hi v180, v4 offset:2448
	ds_write_b16 v180, v5 offset:2592
	ds_write_b16_d16_hi v180, v5 offset:2736
	ds_write_b16 v180, v6 offset:3456
	ds_write_b16_d16_hi v180, v6 offset:3600
	ds_write_b16 v180, v7 offset:3744
	ds_write_b16_d16_hi v180, v7 offset:3888
	v_cvt_pk_bf16_f32 v16, v16, v17
	v_cvt_pk_bf16_f32 v17, v18, v19
	v_cvt_pk_bf16_f32 v18, v20, v21
	v_cvt_pk_bf16_f32 v19, v22, v23
	v_cvt_pk_bf16_f32 v20, v24, v25
	v_cvt_pk_bf16_f32 v21, v26, v27
	v_cvt_pk_bf16_f32 v22, v28, v29
	v_cvt_pk_bf16_f32 v23, v30, v31
	ds_write_b16 v180, v16 offset:4608
	ds_write_b16_d16_hi v180, v16 offset:4752
	ds_write_b16 v180, v17 offset:4896
	ds_write_b16_d16_hi v180, v17 offset:5040
	ds_write_b16 v180, v18 offset:5760
	ds_write_b16_d16_hi v180, v18 offset:5904
	ds_write_b16 v180, v19 offset:6048
	ds_write_b16_d16_hi v180, v19 offset:6192
	ds_write_b16 v180, v20 offset:6912
	ds_write_b16_d16_hi v180, v20 offset:7056
	ds_write_b16 v180, v21 offset:7200
	ds_write_b16_d16_hi v180, v21 offset:7344
	ds_write_b16 v180, v22 offset:8064
	ds_write_b16_d16_hi v180, v22 offset:8208
	ds_write_b16 v180, v23 offset:8352
	ds_write_b16_d16_hi v180, v23 offset:8496
	v_cvt_pk_bf16_f32 v32, v32, v33
	v_cvt_pk_bf16_f32 v33, v34, v35
	v_cvt_pk_bf16_f32 v34, v36, v37
	v_cvt_pk_bf16_f32 v35, v38, v39
	v_cvt_pk_bf16_f32 v36, v40, v41
	v_cvt_pk_bf16_f32 v37, v42, v43
	v_cvt_pk_bf16_f32 v38, v44, v45
	v_cvt_pk_bf16_f32 v39, v46, v47
	ds_write_b16 v180, v32 offset:64
	ds_write_b16_d16_hi v180, v32 offset:208
	ds_write_b16 v180, v33 offset:352
	ds_write_b16_d16_hi v180, v33 offset:496
	ds_write_b16 v180, v34 offset:1216
	ds_write_b16_d16_hi v180, v34 offset:1360
	ds_write_b16 v180, v35 offset:1504
	ds_write_b16_d16_hi v180, v35 offset:1648
	ds_write_b16 v180, v36 offset:2368
	ds_write_b16_d16_hi v180, v36 offset:2512
	ds_write_b16 v180, v37 offset:2656
	ds_write_b16_d16_hi v180, v37 offset:2800
	ds_write_b16 v180, v38 offset:3520
	ds_write_b16_d16_hi v180, v38 offset:3664
	ds_write_b16 v180, v39 offset:3808
	ds_write_b16_d16_hi v180, v39 offset:3952
	v_cvt_pk_bf16_f32 v48, v48, v49
	v_cvt_pk_bf16_f32 v49, v50, v51
	v_cvt_pk_bf16_f32 v50, v52, v53
	v_cvt_pk_bf16_f32 v51, v54, v55
	v_cvt_pk_bf16_f32 v52, v56, v57
	v_cvt_pk_bf16_f32 v53, v58, v59
	v_cvt_pk_bf16_f32 v54, v60, v61
	v_cvt_pk_bf16_f32 v55, v62, v63
	ds_write_b16 v180, v48 offset:4672
	ds_write_b16_d16_hi v180, v48 offset:4816
	ds_write_b16 v180, v49 offset:4960
	ds_write_b16_d16_hi v180, v49 offset:5104
	ds_write_b16 v180, v50 offset:5824
	ds_write_b16_d16_hi v180, v50 offset:5968
	ds_write_b16 v180, v51 offset:6112
	ds_write_b16_d16_hi v180, v51 offset:6256
	ds_write_b16 v180, v52 offset:6976
	ds_write_b16_d16_hi v180, v52 offset:7120
	ds_write_b16 v180, v53 offset:7264
	ds_write_b16_d16_hi v180, v53 offset:7408
	ds_write_b16 v180, v54 offset:8128
	ds_write_b16_d16_hi v180, v54 offset:8272
	ds_write_b16 v180, v55 offset:8416
	ds_write_b16_d16_hi v180, v55 offset:8560
	s_waitcnt lgkmcnt(0)
	ds_read_b128 v[0:3], v198 offset:0
	ds_read_b128 v[4:7], v198 offset:1152
	ds_read_b128 v[8:11], v198 offset:2304
	ds_read_b128 v[12:15], v198 offset:3456
	ds_read_b128 v[16:19], v198 offset:4608
	ds_read_b128 v[20:23], v198 offset:5760
	ds_read_b128 v[24:27], v198 offset:6912
	ds_read_b128 v[28:31], v198 offset:8064
	s_waitcnt lgkmcnt(7)
	global_store_dwordx4 v199, v[0:3], s[38:39]
	s_add_u32 s38, s38, 0x8000
	s_addc_u32 s39, s39, 0
	s_waitcnt lgkmcnt(6)
	global_store_dwordx4 v199, v[4:7], s[38:39]
	s_add_u32 s38, s38, 0x8000
	s_addc_u32 s39, s39, 0
	s_waitcnt lgkmcnt(5)
	global_store_dwordx4 v199, v[8:11], s[38:39]
	s_add_u32 s38, s38, 0x8000
	s_addc_u32 s39, s39, 0
	s_waitcnt lgkmcnt(4)
	global_store_dwordx4 v199, v[12:15], s[38:39]
	s_add_u32 s38, s38, 0x8000
	s_addc_u32 s39, s39, 0
	s_waitcnt lgkmcnt(3)
	global_store_dwordx4 v199, v[16:19], s[38:39]
	s_add_u32 s38, s38, 0x8000
	s_addc_u32 s39, s39, 0
	s_waitcnt lgkmcnt(2)
	global_store_dwordx4 v199, v[20:23], s[38:39]
	s_add_u32 s38, s38, 0x8000
	s_addc_u32 s39, s39, 0
	s_waitcnt lgkmcnt(1)
	global_store_dwordx4 v199, v[24:27], s[38:39]
	s_add_u32 s38, s38, 0x8000
	s_addc_u32 s39, s39, 0
	s_waitcnt lgkmcnt(0)
	global_store_dwordx4 v199, v[28:31], s[38:39]
	s_sub_u32 s38, s38, 229248
	s_subb_u32 s39, s39, 0
	v_cvt_pk_bf16_f32 v64, v64, v65
	v_cvt_pk_bf16_f32 v65, v66, v67
	v_cvt_pk_bf16_f32 v66, v68, v69
	v_cvt_pk_bf16_f32 v67, v70, v71
	v_cvt_pk_bf16_f32 v68, v72, v73
	v_cvt_pk_bf16_f32 v69, v74, v75
	v_cvt_pk_bf16_f32 v70, v76, v77
	v_cvt_pk_bf16_f32 v71, v78, v79
	ds_write_b16 v180, v64 offset:0
	ds_write_b16_d16_hi v180, v64 offset:144
	ds_write_b16 v180, v65 offset:288
	ds_write_b16_d16_hi v180, v65 offset:432
	ds_write_b16 v180, v66 offset:1152
	ds_write_b16_d16_hi v180, v66 offset:1296
	ds_write_b16 v180, v67 offset:1440
	ds_write_b16_d16_hi v180, v67 offset:1584
	ds_write_b16 v180, v68 offset:2304
	ds_write_b16_d16_hi v180, v68 offset:2448
	ds_write_b16 v180, v69 offset:2592
	ds_write_b16_d16_hi v180, v69 offset:2736
	ds_write_b16 v180, v70 offset:3456
	ds_write_b16_d16_hi v180, v70 offset:3600
	ds_write_b16 v180, v71 offset:3744
	ds_write_b16_d16_hi v180, v71 offset:3888
	v_cvt_pk_bf16_f32 v80, v80, v81
	v_cvt_pk_bf16_f32 v81, v82, v83
	v_cvt_pk_bf16_f32 v82, v84, v85
	v_cvt_pk_bf16_f32 v83, v86, v87
	v_cvt_pk_bf16_f32 v84, v88, v89
	v_cvt_pk_bf16_f32 v85, v90, v91
	v_cvt_pk_bf16_f32 v86, v92, v93
	v_cvt_pk_bf16_f32 v87, v94, v95
	ds_write_b16 v180, v80 offset:4608
	ds_write_b16_d16_hi v180, v80 offset:4752
	ds_write_b16 v180, v81 offset:4896
	ds_write_b16_d16_hi v180, v81 offset:5040
	ds_write_b16 v180, v82 offset:5760
	ds_write_b16_d16_hi v180, v82 offset:5904
	ds_write_b16 v180, v83 offset:6048
	ds_write_b16_d16_hi v180, v83 offset:6192
	ds_write_b16 v180, v84 offset:6912
	ds_write_b16_d16_hi v180, v84 offset:7056
	ds_write_b16 v180, v85 offset:7200
	ds_write_b16_d16_hi v180, v85 offset:7344
	ds_write_b16 v180, v86 offset:8064
	ds_write_b16_d16_hi v180, v86 offset:8208
	ds_write_b16 v180, v87 offset:8352
	ds_write_b16_d16_hi v180, v87 offset:8496
	v_cvt_pk_bf16_f32 v96, v96, v97
	v_cvt_pk_bf16_f32 v97, v98, v99
	v_cvt_pk_bf16_f32 v98, v100, v101
	v_cvt_pk_bf16_f32 v99, v102, v103
	v_cvt_pk_bf16_f32 v100, v104, v105
	v_cvt_pk_bf16_f32 v101, v106, v107
	v_cvt_pk_bf16_f32 v102, v108, v109
	v_cvt_pk_bf16_f32 v103, v110, v111
	ds_write_b16 v180, v96 offset:64
	ds_write_b16_d16_hi v180, v96 offset:208
	ds_write_b16 v180, v97 offset:352
	ds_write_b16_d16_hi v180, v97 offset:496
	ds_write_b16 v180, v98 offset:1216
	ds_write_b16_d16_hi v180, v98 offset:1360
	ds_write_b16 v180, v99 offset:1504
	ds_write_b16_d16_hi v180, v99 offset:1648
	ds_write_b16 v180, v100 offset:2368
	ds_write_b16_d16_hi v180, v100 offset:2512
	ds_write_b16 v180, v101 offset:2656
	ds_write_b16_d16_hi v180, v101 offset:2800
	ds_write_b16 v180, v102 offset:3520
	ds_write_b16_d16_hi v180, v102 offset:3664
	ds_write_b16 v180, v103 offset:3808
	ds_write_b16_d16_hi v180, v103 offset:3952
	v_cvt_pk_bf16_f32 v112, v112, v113
	v_cvt_pk_bf16_f32 v113, v114, v115
	v_cvt_pk_bf16_f32 v114, v116, v117
	v_cvt_pk_bf16_f32 v115, v118, v119
	v_cvt_pk_bf16_f32 v116, v120, v121
	v_cvt_pk_bf16_f32 v117, v122, v123
	v_cvt_pk_bf16_f32 v118, v124, v125
	v_cvt_pk_bf16_f32 v119, v126, v127
	ds_write_b16 v180, v112 offset:4672
	ds_write_b16_d16_hi v180, v112 offset:4816
	ds_write_b16 v180, v113 offset:4960
	ds_write_b16_d16_hi v180, v113 offset:5104
	ds_write_b16 v180, v114 offset:5824
	ds_write_b16_d16_hi v180, v114 offset:5968
	ds_write_b16 v180, v115 offset:6112
	ds_write_b16_d16_hi v180, v115 offset:6256
	ds_write_b16 v180, v116 offset:6976
	ds_write_b16_d16_hi v180, v116 offset:7120
	ds_write_b16 v180, v117 offset:7264
	ds_write_b16_d16_hi v180, v117 offset:7408
	ds_write_b16 v180, v118 offset:8128
	ds_write_b16_d16_hi v180, v118 offset:8272
	ds_write_b16 v180, v119 offset:8416
	ds_write_b16_d16_hi v180, v119 offset:8560
	s_waitcnt lgkmcnt(0)
	ds_read_b128 v[64:67], v198 offset:0
	ds_read_b128 v[68:71], v198 offset:1152
	ds_read_b128 v[72:75], v198 offset:2304
	ds_read_b128 v[76:79], v198 offset:3456
	ds_read_b128 v[80:83], v198 offset:4608
	ds_read_b128 v[84:87], v198 offset:5760
	ds_read_b128 v[88:91], v198 offset:6912
	ds_read_b128 v[92:95], v198 offset:8064
	s_waitcnt lgkmcnt(7)
	global_store_dwordx4 v199, v[64:67], s[38:39]
	s_add_u32 s38, s38, 0x8000
	s_addc_u32 s39, s39, 0
	s_waitcnt lgkmcnt(6)
	global_store_dwordx4 v199, v[68:71], s[38:39]
	s_add_u32 s38, s38, 0x8000
	s_addc_u32 s39, s39, 0
	s_waitcnt lgkmcnt(5)
	global_store_dwordx4 v199, v[72:75], s[38:39]
	s_add_u32 s38, s38, 0x8000
	s_addc_u32 s39, s39, 0
	s_waitcnt lgkmcnt(4)
	global_store_dwordx4 v199, v[76:79], s[38:39]
	s_add_u32 s38, s38, 0x8000
	s_addc_u32 s39, s39, 0
	s_waitcnt lgkmcnt(3)
	global_store_dwordx4 v199, v[80:83], s[38:39]
	s_add_u32 s38, s38, 0x8000
	s_addc_u32 s39, s39, 0
	s_waitcnt lgkmcnt(2)
	global_store_dwordx4 v199, v[84:87], s[38:39]
	s_add_u32 s38, s38, 0x8000
	s_addc_u32 s39, s39, 0
	s_waitcnt lgkmcnt(1)
	global_store_dwordx4 v199, v[88:91], s[38:39]
	s_add_u32 s38, s38, 0x8000
	s_addc_u32 s39, s39, 0
	s_waitcnt lgkmcnt(0)
	global_store_dwordx4 v199, v[92:95], s[38:39]
